# SrcA fragment quads at acc bank phase (2), SrcB quads at phase 0, 7 GEMM loops; + saddr, trim, stagger
# baseline (speedup 1.0000x reference)
; #define PG8_STAGE(bufoff, gbase, voff) do { _Pragma("unroll") for (int _i = 0; _i < 2; ++_i) \
;         __builtin_amdgcn_global_load_lds((const unsigned*)((const char*)(gbase) + (voff)[_i]), (LAS unsigned*)(lds + (bufoff) + ldsw + _i * 8192), 16, 0, 0); } while (0)
; #define PG8_LDA(dst, b, h) do { _Pragma("unroll") for (int m = 0; m < 4; ++m) _Pragma("unroll") for (int k = 0; k < 2; ++k) dst[m][k] = *(const LAS bf16x8*)(lds + PG8_SA(b, h) + aoff + m * 2048 + k * 1024); } while (0)
; #define PG8_LDB(dst, b, h) do { _Pragma("unroll") for (int n = 0; n < 2; ++n) _Pragma("unroll") for (int k = 0; k < 2; ++k) dst[n][k] = *(const LAS bf16x8*)(lds + PG8_SB(b, h) + boff + n * 2048 + k * 1024); } while (0)
; #define PG8_MMA(ai, bj, At, Bt) do { __builtin_amdgcn_s_setprio(1); _Pragma("unroll") for (int m = 0; m < 4; ++m) _Pragma("unroll") for (int n = 0; n < 2; ++n) _Pragma("unroll") for (int k = 0; k < 2; ++k) \
;         acc[ai][bj][m][n] = __builtin_amdgcn_mfma_f32_16x16x32_bf16(Bt[n][k], At[m][k], acc[ai][bj][m][n], 0, 0, 0); __builtin_amdgcn_s_setprio(0); } while (0)
; #define PG8_WAIT_V(n) asm volatile("s_waitcnt vmcnt(" #n ")" ::: "memory")
; #define PG8_WAIT_L(n) asm volatile("s_waitcnt lgkmcnt(" #n ")" ::: "memory")
; #define PG8_BAR __builtin_amdgcn_s_barrier()
; template <class Epi>
; __device__ __forceinline__ void gemm_phase(LAS unsigned char* lds, const Gemm g, const StaticOrder& S, const Epi& E) {
;     ...
;             const bool last = (t == nt - 2);
;             const char* a1 = cA + (size_t)(t + 1) * kstep;
;             const char* a2 = last ? nA : cA + (size_t)(t + 2) * kstep; const char* b2 = last ? nB : cB + (size_t)(t + 2) * kstep;
;             const char* a3 = a2 + kstep; const char* b3 = b2 + kstep;
;             if constexpr (Epi::MIDK > 0) { if (t == Epi::MIDK) E.mid(acc, cur, wr, wc, fr, fq); }
;             PG8_LDB(B0, 0, 0); PG8_LDB(B1, 0, 1); PG8_SCHED; PG8_LDA(At, 0, 0); PG8_STAGE(PG8_SA(1, 1), a1 + hstep, voffA);
;             PG8_WAIT_V(8); PG8_WAIT_L(0); PG8_BAR; PG8_MMA(0, 0, At, B0); PG8_MMA(0, 1, At, B1); PG8_BAR; PG8_SCHED;
;             PG8_LDA(At, 0, 1); PG8_STAGE(PG8_SB(0, 0), b2, voffB); PG8_STAGE(PG8_SB(0, 1), b2 + hstep, voffB); PG8_STAGE(PG8_SA(0, 0), a2, voffA);
;             PG8_WAIT_V(8); PG8_WAIT_L(0); PG8_BAR; PG8_MMA(1, 0, At, B0); PG8_MMA(1, 1, At, B1); PG8_BAR; PG8_SCHED;
.LBB0_134:
	ds_read_b128 v[158:161], v150
	ds_read_b128 v[162:165], v150 offset:1024
	ds_read_b128 v[166:169], v150 offset:2048
	ds_read_b128 v[174:177], v150 offset:3072
	ds_read_b128 v[178:181], v151
	ds_read_b128 v[182:185], v151 offset:1024
	ds_read_b128 v[186:189], v151 offset:2048
	ds_read_b128 v[190:193], v151 offset:3072
	s_add_u32 s66, s64, 0xfffc0080
	s_addc_u32 s67, s65, -1
	s_cmp_eq_u32 s92, 12
	s_cselect_b32 s69, s87, s67
	s_cselect_b32 s68, s88, s66
	s_cselect_b32 s67, s47, s91
	s_cselect_b32 s66, s89, s90
	s_add_i32 m0, s61, 0xc000
	ds_read_b128 v[200:203], v152
	ds_read_b128 v[204:207], v152 offset:1024
	ds_read_b128 v[208:211], v152 offset:2048
	ds_read_b128 v[212:215], v152 offset:3072
	ds_read_b128 v[216:219], v152 offset:4096
	ds_read_b128 v[220:223], v152 offset:5120
	ds_read_b128 v[224:227], v152 offset:6144
	ds_read_b128 v[228:231], v152 offset:7168
	global_load_lds_dwordx4 v140, s[64:65]
	s_add_i32 m0, s61, 0xe000
	s_nop 0
	global_load_lds_dwordx4 v142, s[64:65]
	s_waitcnt vmcnt(8)
	s_waitcnt lgkmcnt(0)
	s_setprio 1
	s_barrier
	v_mfma_f32_16x16x32_bf16 v[126:129], v[158:161], v[200:203], v[126:129]
	v_mfma_f32_16x16x32_bf16 v[118:121], v[166:169], v[200:203], v[118:121]
	v_mfma_f32_16x16x32_bf16 v[110:113], v[158:161], v[208:211], v[110:113]
	v_mfma_f32_16x16x32_bf16 v[102:105], v[166:169], v[208:211], v[102:105]
	v_mfma_f32_16x16x32_bf16 v[94:97], v[158:161], v[216:219], v[94:97]
	v_mfma_f32_16x16x32_bf16 v[86:89], v[166:169], v[216:219], v[86:89]
	v_mfma_f32_16x16x32_bf16 v[78:81], v[158:161], v[224:227], v[78:81]
	v_mfma_f32_16x16x32_bf16 v[70:73], v[166:169], v[224:227], v[70:73]
	v_mfma_f32_16x16x32_bf16 v[126:129], v[162:165], v[204:207], v[126:129]
	v_mfma_f32_16x16x32_bf16 v[118:121], v[174:177], v[204:207], v[118:121]
	v_mfma_f32_16x16x32_bf16 v[110:113], v[162:165], v[212:215], v[110:113]
	v_mfma_f32_16x16x32_bf16 v[102:105], v[174:177], v[212:215], v[102:105]
	v_mfma_f32_16x16x32_bf16 v[94:97], v[162:165], v[220:223], v[94:97]
	v_mfma_f32_16x16x32_bf16 v[86:89], v[174:177], v[220:223], v[86:89]
	v_mfma_f32_16x16x32_bf16 v[78:81], v[162:165], v[228:231], v[78:81]
	v_mfma_f32_16x16x32_bf16 v[70:73], v[174:177], v[228:231], v[70:73]
	v_mfma_f32_16x16x32_bf16 v[122:125], v[178:181], v[200:203], v[122:125]
	v_mfma_f32_16x16x32_bf16 v[114:117], v[186:189], v[200:203], v[114:117]
	v_mfma_f32_16x16x32_bf16 v[106:109], v[178:181], v[208:211], v[106:109]
	v_mfma_f32_16x16x32_bf16 v[98:101], v[186:189], v[208:211], v[98:101]
	v_mfma_f32_16x16x32_bf16 v[90:93], v[178:181], v[216:219], v[90:93]
	v_mfma_f32_16x16x32_bf16 v[82:85], v[186:189], v[216:219], v[82:85]
	v_mfma_f32_16x16x32_bf16 v[74:77], v[178:181], v[224:227], v[74:77]
	v_mfma_f32_16x16x32_bf16 v[66:69], v[186:189], v[224:227], v[66:69]
	v_mfma_f32_16x16x32_bf16 v[122:125], v[182:185], v[204:207], v[122:125]
	v_mfma_f32_16x16x32_bf16 v[114:117], v[190:193], v[204:207], v[114:117]
	v_mfma_f32_16x16x32_bf16 v[106:109], v[182:185], v[212:215], v[106:109]
	v_mfma_f32_16x16x32_bf16 v[98:101], v[190:193], v[212:215], v[98:101]
	v_mfma_f32_16x16x32_bf16 v[90:93], v[182:185], v[220:223], v[90:93]
	v_mfma_f32_16x16x32_bf16 v[82:85], v[190:193], v[220:223], v[82:85]
	v_mfma_f32_16x16x32_bf16 v[74:77], v[182:185], v[228:231], v[74:77]
	v_mfma_f32_16x16x32_bf16 v[66:69], v[190:193], v[228:231], v[66:69]
	s_barrier
	s_setprio 0
	s_add_u32 s98, s66, s8
	s_addc_u32 s99, s67, s9
	s_add_u32 s100, s68, s8
	s_addc_u32 s101, s69, s9
	s_add_i32 s93, s83, s6
	s_mov_b32 m0, s93
	ds_read_b128 v[200:203], v152 offset:16384
	ds_read_b128 v[204:207], v152 offset:17408
	ds_read_b128 v[208:211], v152 offset:18432
	ds_read_b128 v[212:215], v152 offset:19456
	ds_read_b128 v[216:219], v152 offset:20480
	ds_read_b128 v[220:223], v152 offset:21504
	ds_read_b128 v[224:227], v152 offset:22528
	ds_read_b128 v[228:231], v152 offset:23552
	global_load_lds_dwordx4 v132, s[66:67]
	s_add_i32 m0, s93, 0x2000
	s_add_u32 s94, s66, 0x40000
	s_addc_u32 s95, s67, 0
	s_add_i32 s93, s84, s6
	global_load_lds_dwordx4 v136, s[66:67]
	s_mov_b32 m0, s93
	s_nop 0
	global_load_lds_dwordx4 v132, s[94:95]
	s_add_i32 m0, s93, 0x2000
	s_nop 0
	global_load_lds_dwordx4 v136, s[94:95]
	s_mov_b32 m0, s61
	s_nop 0
	global_load_lds_dwordx4 v130, s[68:69]
	s_mov_b32 m0, s63
	s_nop 0
	global_load_lds_dwordx4 v134, s[68:69]
	s_waitcnt vmcnt(8)
	s_waitcnt lgkmcnt(0)
	s_setprio 1
	s_barrier
	v_mfma_f32_16x16x32_bf16 v[62:65], v[158:161], v[200:203], v[62:65]
	v_mfma_f32_16x16x32_bf16 v[54:57], v[166:169], v[200:203], v[54:57]
	v_mfma_f32_16x16x32_bf16 v[46:49], v[158:161], v[208:211], v[46:49]
	v_mfma_f32_16x16x32_bf16 v[38:41], v[166:169], v[208:211], v[38:41]
	v_mfma_f32_16x16x32_bf16 v[30:33], v[158:161], v[216:219], v[30:33]
	v_mfma_f32_16x16x32_bf16 v[22:25], v[166:169], v[216:219], v[22:25]
	v_mfma_f32_16x16x32_bf16 v[14:17], v[158:161], v[224:227], v[14:17]
	v_mfma_f32_16x16x32_bf16 v[6:9], v[166:169], v[224:227], v[6:9]
	v_mfma_f32_16x16x32_bf16 v[62:65], v[162:165], v[204:207], v[62:65]
	v_mfma_f32_16x16x32_bf16 v[54:57], v[174:177], v[204:207], v[54:57]
	v_mfma_f32_16x16x32_bf16 v[46:49], v[162:165], v[212:215], v[46:49]
	v_mfma_f32_16x16x32_bf16 v[38:41], v[174:177], v[212:215], v[38:41]
	v_mfma_f32_16x16x32_bf16 v[30:33], v[162:165], v[220:223], v[30:33]
	v_mfma_f32_16x16x32_bf16 v[22:25], v[174:177], v[220:223], v[22:25]
	v_mfma_f32_16x16x32_bf16 v[14:17], v[162:165], v[228:231], v[14:17]
	v_mfma_f32_16x16x32_bf16 v[6:9], v[174:177], v[228:231], v[6:9]
	v_mfma_f32_16x16x32_bf16 v[58:61], v[178:181], v[200:203], v[58:61]
	v_mfma_f32_16x16x32_bf16 v[50:53], v[186:189], v[200:203], v[50:53]
	v_mfma_f32_16x16x32_bf16 v[42:45], v[178:181], v[208:211], v[42:45]
	v_mfma_f32_16x16x32_bf16 v[34:37], v[186:189], v[208:211], v[34:37]
	v_mfma_f32_16x16x32_bf16 v[26:29], v[178:181], v[216:219], v[26:29]
	v_mfma_f32_16x16x32_bf16 v[18:21], v[186:189], v[216:219], v[18:21]
	v_mfma_f32_16x16x32_bf16 v[10:13], v[178:181], v[224:227], v[10:13]
	v_mfma_f32_16x16x32_bf16 v[2:5], v[186:189], v[224:227], v[2:5]
	v_mfma_f32_16x16x32_bf16 v[58:61], v[182:185], v[204:207], v[58:61]
	v_mfma_f32_16x16x32_bf16 v[50:53], v[190:193], v[204:207], v[50:53]
	v_mfma_f32_16x16x32_bf16 v[42:45], v[182:185], v[212:215], v[42:45]
	v_mfma_f32_16x16x32_bf16 v[34:37], v[190:193], v[212:215], v[34:37]
	v_mfma_f32_16x16x32_bf16 v[26:29], v[182:185], v[220:223], v[26:29]
	v_mfma_f32_16x16x32_bf16 v[18:21], v[190:193], v[220:223], v[18:21]
	v_mfma_f32_16x16x32_bf16 v[10:13], v[182:185], v[228:231], v[10:13]
	v_mfma_f32_16x16x32_bf16 v[2:5], v[190:193], v[228:231], v[2:5]
	s_barrier
; #define PG8_STAGE(bufoff, gbase, voff) do { _Pragma("unroll") for (int _i = 0; _i < 2; ++_i) \
;         __builtin_amdgcn_global_load_lds((const unsigned*)((const char*)(gbase) + (voff)[_i]), (LAS unsigned*)(lds + (bufoff) + ldsw + _i * 8192), 16, 0, 0); } while (0)
; #define PG8_LDA(dst, b, h) do { _Pragma("unroll") for (int m = 0; m < 4; ++m) _Pragma("unroll") for (int k = 0; k < 2; ++k) dst[m][k] = *(const LAS bf16x8*)(lds + PG8_SA(b, h) + aoff + m * 2048 + k * 1024); } while (0)
; #define PG8_LDB(dst, b, h) do { _Pragma("unroll") for (int n = 0; n < 2; ++n) _Pragma("unroll") for (int k = 0; k < 2; ++k) dst[n][k] = *(const LAS bf16x8*)(lds + PG8_SB(b, h) + boff + n * 2048 + k * 1024); } while (0)
; #define PG8_MMA(ai, bj, At, Bt) do { __builtin_amdgcn_s_setprio(1); _Pragma("unroll") for (int m = 0; m < 4; ++m) _Pragma("unroll") for (int n = 0; n < 2; ++n) _Pragma("unroll") for (int k = 0; k < 2; ++k) \
;         acc[ai][bj][m][n] = __builtin_amdgcn_mfma_f32_16x16x32_bf16(Bt[n][k], At[m][k], acc[ai][bj][m][n], 0, 0, 0); __builtin_amdgcn_s_setprio(0); } while (0)
; #define PG8_WAIT_V(n) asm volatile("s_waitcnt vmcnt(" #n ")" ::: "memory")
; #define PG8_WAIT_L(n) asm volatile("s_waitcnt lgkmcnt(" #n ")" ::: "memory")
; #define PG8_BAR __builtin_amdgcn_s_barrier()
; #define PG8_SCHED __builtin_amdgcn_sched_barrier(0)
; template <class Epi>
; __device__ __forceinline__ void gemm_phase(LAS unsigned char* lds, const Gemm g, const StaticOrder& S, const Epi& E) {
;     ...
;             PG8_LDB(B0, 1, 0); PG8_LDB(B1, 1, 1); PG8_SCHED; PG8_LDA(At, 1, 0); PG8_STAGE(PG8_SA(0, 1), a2 + hstep, voffA);
;             PG8_WAIT_V(8); PG8_WAIT_L(0); PG8_BAR; PG8_MMA(0, 0, At, B0); PG8_MMA(0, 1, At, B1); PG8_BAR; PG8_SCHED;
;             PG8_LDA(At, 1, 1); PG8_STAGE(PG8_SB(1, 0), b3, voffB); PG8_STAGE(PG8_SB(1, 1), b3 + hstep, voffB); PG8_STAGE(PG8_SA(1, 0), a3, voffA);
;             PG8_WAIT_V(8); PG8_WAIT_L(0); PG8_BAR; PG8_MMA(1, 0, At, B0); PG8_MMA(1, 1, At, B1); PG8_BAR; PG8_SCHED;
;         }
	s_setprio 0
	s_add_i32 s93, 0, 0x18000
	s_add_i32 s94, 0, 0x1c000
	v_add_u32_e32 v174, s93, v148
	v_add_u32_e32 v190, s94, v148
	ds_read_b128 v[158:161], v174
	ds_read_b128 v[162:165], v174 offset:1024
	ds_read_b128 v[166:169], v174 offset:2048
	ds_read_b128 v[174:177], v174 offset:3072
	ds_read_b128 v[178:181], v190
	ds_read_b128 v[182:185], v190 offset:1024
	ds_read_b128 v[186:189], v190 offset:2048
	ds_read_b128 v[190:193], v190 offset:3072
	s_add_u32 s68, s68, 0x40000
	s_addc_u32 s69, s69, 0
	s_mov_b32 m0, s77
	ds_read_b128 v[200:203], v152 offset:32768
	ds_read_b128 v[204:207], v152 offset:33792
	ds_read_b128 v[208:211], v152 offset:34816
	ds_read_b128 v[212:215], v152 offset:35840
	ds_read_b128 v[216:219], v152 offset:36864
	ds_read_b128 v[220:223], v152 offset:37888
	ds_read_b128 v[224:227], v152 offset:38912
	ds_read_b128 v[228:231], v152 offset:39936
	global_load_lds_dwordx4 v130, s[68:69]
	s_mov_b32 m0, s78
	s_nop 0
	global_load_lds_dwordx4 v134, s[68:69]
	s_waitcnt vmcnt(8)
	s_waitcnt lgkmcnt(0)
	s_setprio 1
	s_barrier
	v_mfma_f32_16x16x32_bf16 v[126:129], v[158:161], v[200:203], v[126:129]
	v_mfma_f32_16x16x32_bf16 v[118:121], v[166:169], v[200:203], v[118:121]
	v_mfma_f32_16x16x32_bf16 v[110:113], v[158:161], v[208:211], v[110:113]
	v_mfma_f32_16x16x32_bf16 v[102:105], v[166:169], v[208:211], v[102:105]
	v_mfma_f32_16x16x32_bf16 v[94:97], v[158:161], v[216:219], v[94:97]
	v_mfma_f32_16x16x32_bf16 v[86:89], v[166:169], v[216:219], v[86:89]
	v_mfma_f32_16x16x32_bf16 v[78:81], v[158:161], v[224:227], v[78:81]
	v_mfma_f32_16x16x32_bf16 v[70:73], v[166:169], v[224:227], v[70:73]
	v_mfma_f32_16x16x32_bf16 v[126:129], v[162:165], v[204:207], v[126:129]
	v_mfma_f32_16x16x32_bf16 v[118:121], v[174:177], v[204:207], v[118:121]
	v_mfma_f32_16x16x32_bf16 v[110:113], v[162:165], v[212:215], v[110:113]
	v_mfma_f32_16x16x32_bf16 v[102:105], v[174:177], v[212:215], v[102:105]
	v_mfma_f32_16x16x32_bf16 v[94:97], v[162:165], v[220:223], v[94:97]
	v_mfma_f32_16x16x32_bf16 v[86:89], v[174:177], v[220:223], v[86:89]
	v_mfma_f32_16x16x32_bf16 v[78:81], v[162:165], v[228:231], v[78:81]
	v_mfma_f32_16x16x32_bf16 v[70:73], v[174:177], v[228:231], v[70:73]
	v_mfma_f32_16x16x32_bf16 v[122:125], v[178:181], v[200:203], v[122:125]
	v_mfma_f32_16x16x32_bf16 v[114:117], v[186:189], v[200:203], v[114:117]
	v_mfma_f32_16x16x32_bf16 v[106:109], v[178:181], v[208:211], v[106:109]
	v_mfma_f32_16x16x32_bf16 v[98:101], v[186:189], v[208:211], v[98:101]
	v_mfma_f32_16x16x32_bf16 v[90:93], v[178:181], v[216:219], v[90:93]
	v_mfma_f32_16x16x32_bf16 v[82:85], v[186:189], v[216:219], v[82:85]
	v_mfma_f32_16x16x32_bf16 v[74:77], v[178:181], v[224:227], v[74:77]
	v_mfma_f32_16x16x32_bf16 v[66:69], v[186:189], v[224:227], v[66:69]
	v_mfma_f32_16x16x32_bf16 v[122:125], v[182:185], v[204:207], v[122:125]
	v_mfma_f32_16x16x32_bf16 v[114:117], v[190:193], v[204:207], v[114:117]
	v_mfma_f32_16x16x32_bf16 v[106:109], v[182:185], v[212:215], v[106:109]
	v_mfma_f32_16x16x32_bf16 v[98:101], v[190:193], v[212:215], v[98:101]
	v_mfma_f32_16x16x32_bf16 v[90:93], v[182:185], v[220:223], v[90:93]
	v_mfma_f32_16x16x32_bf16 v[82:85], v[190:193], v[220:223], v[82:85]
	v_mfma_f32_16x16x32_bf16 v[74:77], v[182:185], v[228:231], v[74:77]
	v_mfma_f32_16x16x32_bf16 v[66:69], v[190:193], v[228:231], v[66:69]
	s_barrier
	s_setprio 0
	s_add_i32 s68, s93, s6
	s_mov_b32 m0, s68
	ds_read_b128 v[200:203], v152 offset:49152
	ds_read_b128 v[204:207], v152 offset:50176
	ds_read_b128 v[208:211], v152 offset:51200
	ds_read_b128 v[212:215], v152 offset:52224
	ds_read_b128 v[216:219], v152 offset:53248
	ds_read_b128 v[220:223], v152 offset:54272
	ds_read_b128 v[224:227], v152 offset:55296
	ds_read_b128 v[228:231], v152 offset:56320
	global_load_lds_dwordx4 v132, s[98:99]
	s_add_i32 m0, s68, 0x2000
	s_add_u32 s66, s66, 0x40080
	s_addc_u32 s67, s67, 0
	s_add_i32 s68, s94, s6
	global_load_lds_dwordx4 v136, s[98:99]
	s_mov_b32 m0, s68
	s_nop 0
	global_load_lds_dwordx4 v132, s[66:67]
	s_add_i32 m0, s68, 0x2000
	s_nop 0
	global_load_lds_dwordx4 v136, s[66:67]
	s_mov_b32 m0, s79
	s_nop 0
	global_load_lds_dwordx4 v130, s[100:101]
	s_mov_b32 m0, s80
	s_nop 0
	global_load_lds_dwordx4 v134, s[100:101]
	s_waitcnt vmcnt(8)
	s_waitcnt lgkmcnt(0)
	s_setprio 1
	s_barrier
	v_mfma_f32_16x16x32_bf16 v[62:65], v[158:161], v[200:203], v[62:65]
	v_mfma_f32_16x16x32_bf16 v[54:57], v[166:169], v[200:203], v[54:57]
	v_mfma_f32_16x16x32_bf16 v[46:49], v[158:161], v[208:211], v[46:49]
	v_mfma_f32_16x16x32_bf16 v[38:41], v[166:169], v[208:211], v[38:41]
	v_mfma_f32_16x16x32_bf16 v[30:33], v[158:161], v[216:219], v[30:33]
	v_mfma_f32_16x16x32_bf16 v[22:25], v[166:169], v[216:219], v[22:25]
	v_mfma_f32_16x16x32_bf16 v[14:17], v[158:161], v[224:227], v[14:17]
	v_mfma_f32_16x16x32_bf16 v[6:9], v[166:169], v[224:227], v[6:9]
	v_mfma_f32_16x16x32_bf16 v[62:65], v[162:165], v[204:207], v[62:65]
	v_mfma_f32_16x16x32_bf16 v[54:57], v[174:177], v[204:207], v[54:57]
	v_mfma_f32_16x16x32_bf16 v[46:49], v[162:165], v[212:215], v[46:49]
	v_mfma_f32_16x16x32_bf16 v[38:41], v[174:177], v[212:215], v[38:41]
	v_mfma_f32_16x16x32_bf16 v[30:33], v[162:165], v[220:223], v[30:33]
	v_mfma_f32_16x16x32_bf16 v[22:25], v[174:177], v[220:223], v[22:25]
	v_mfma_f32_16x16x32_bf16 v[14:17], v[162:165], v[228:231], v[14:17]
	v_mfma_f32_16x16x32_bf16 v[6:9], v[174:177], v[228:231], v[6:9]
	v_mfma_f32_16x16x32_bf16 v[58:61], v[178:181], v[200:203], v[58:61]
	v_mfma_f32_16x16x32_bf16 v[50:53], v[186:189], v[200:203], v[50:53]
	v_mfma_f32_16x16x32_bf16 v[42:45], v[178:181], v[208:211], v[42:45]
	v_mfma_f32_16x16x32_bf16 v[34:37], v[186:189], v[208:211], v[34:37]
	v_mfma_f32_16x16x32_bf16 v[26:29], v[178:181], v[216:219], v[26:29]
	v_mfma_f32_16x16x32_bf16 v[18:21], v[186:189], v[216:219], v[18:21]
	v_mfma_f32_16x16x32_bf16 v[10:13], v[178:181], v[224:227], v[10:13]
	v_mfma_f32_16x16x32_bf16 v[2:5], v[186:189], v[224:227], v[2:5]
	v_mfma_f32_16x16x32_bf16 v[58:61], v[182:185], v[204:207], v[58:61]
	v_mfma_f32_16x16x32_bf16 v[50:53], v[190:193], v[204:207], v[50:53]
	v_mfma_f32_16x16x32_bf16 v[42:45], v[182:185], v[212:215], v[42:45]
	v_mfma_f32_16x16x32_bf16 v[34:37], v[190:193], v[212:215], v[34:37]
	v_mfma_f32_16x16x32_bf16 v[26:29], v[182:185], v[220:223], v[26:29]
	v_mfma_f32_16x16x32_bf16 v[18:21], v[190:193], v[220:223], v[18:21]
	v_mfma_f32_16x16x32_bf16 v[10:13], v[182:185], v[228:231], v[10:13]
	v_mfma_f32_16x16x32_bf16 v[2:5], v[190:193], v[228:231], v[2:5]
	s_barrier
	s_setprio 0
	s_add_i32 s92, s92, 2
	s_add_u32 s64, s64, 0x100
	s_addc_u32 s65, s65, 0
	s_add_u32 s90, s90, 0x100
	s_addc_u32 s91, s91, 0
	s_cmp_gt_u32 s92, 13
	s_cbranch_scc0 .LBB0_134
	s_and_b64 vcc, exec, s[38:39]
	s_cbranch_vccz .LBB0_137
	s_barrier

; #define PG8_STAGE(bufoff, gbase, voff) do { _Pragma("unroll") for (int _i = 0; _i < 2; ++_i) \
;         __builtin_amdgcn_global_load_lds((const unsigned*)((const char*)(gbase) + (voff)[_i]), (LAS unsigned*)(lds + (bufoff) + ldsw + _i * 8192), 16, 0, 0); } while (0)
; #define PG8_LDA(dst, b, h) do { _Pragma("unroll") for (int m = 0; m < 4; ++m) _Pragma("unroll") for (int k = 0; k < 2; ++k) dst[m][k] = *(const LAS bf16x8*)(lds + PG8_SA(b, h) + aoff + m * 2048 + k * 1024); } while (0)
; #define PG8_LDB(dst, b, h) do { _Pragma("unroll") for (int n = 0; n < 2; ++n) _Pragma("unroll") for (int k = 0; k < 2; ++k) dst[n][k] = *(const LAS bf16x8*)(lds + PG8_SB(b, h) + boff + n * 2048 + k * 1024); } while (0)
; #define PG8_MMA(ai, bj, At, Bt) do { __builtin_amdgcn_s_setprio(1); _Pragma("unroll") for (int m = 0; m < 4; ++m) _Pragma("unroll") for (int n = 0; n < 2; ++n) _Pragma("unroll") for (int k = 0; k < 2; ++k) \
;         acc[ai][bj][m][n] = __builtin_amdgcn_mfma_f32_16x16x32_bf16(Bt[n][k], At[m][k], acc[ai][bj][m][n], 0, 0, 0); __builtin_amdgcn_s_setprio(0); } while (0)
; #define PG8_WAIT_V(n) asm volatile("s_waitcnt vmcnt(" #n ")" ::: "memory")
; #define PG8_WAIT_L(n) asm volatile("s_waitcnt lgkmcnt(" #n ")" ::: "memory")
; #define PG8_BAR __builtin_amdgcn_s_barrier()
; template <class Epi>
; __device__ __forceinline__ void gemm_phase(LAS unsigned char* lds, const Gemm g, const StaticOrder& S, const Epi& E) {
;     ...
;             const bool last = (t == nt - 2);
;             const char* a1 = cA + (size_t)(t + 1) * kstep;
;             const char* a2 = last ? nA : cA + (size_t)(t + 2) * kstep; const char* b2 = last ? nB : cB + (size_t)(t + 2) * kstep;
;             const char* a3 = a2 + kstep; const char* b3 = b2 + kstep;
;             if constexpr (Epi::MIDK > 0) { if (t == Epi::MIDK) E.mid(acc, cur, wr, wc, fr, fq); }
;             PG8_LDB(B0, 0, 0); PG8_LDB(B1, 0, 1); PG8_SCHED; PG8_LDA(At, 0, 0); PG8_STAGE(PG8_SA(1, 1), a1 + hstep, voffA);
;             PG8_WAIT_V(8); PG8_WAIT_L(0); PG8_BAR; PG8_MMA(0, 0, At, B0); PG8_MMA(0, 1, At, B1); PG8_BAR; PG8_SCHED;
;             PG8_LDA(At, 0, 1); PG8_STAGE(PG8_SB(0, 0), b2, voffB); PG8_STAGE(PG8_SB(0, 1), b2 + hstep, voffB); PG8_STAGE(PG8_SA(0, 0), a2, voffA);
;             PG8_WAIT_V(8); PG8_WAIT_L(0); PG8_BAR; PG8_MMA(1, 0, At, B0); PG8_MMA(1, 1, At, B1); PG8_BAR; PG8_SCHED;
.LBB0_221:
	ds_read_b128 v[130:133], v162
	ds_read_b128 v[134:137], v162 offset:1024
	ds_read_b128 v[154:157], v162 offset:2048
	ds_read_b128 v[166:169], v162 offset:3072
	ds_read_b128 v[174:177], v163
	ds_read_b128 v[178:181], v163 offset:1024
	ds_read_b128 v[182:185], v163 offset:2048
	ds_read_b128 v[186:189], v163 offset:3072
	s_add_u32 s48, s46, 0xfff50080
	s_addc_u32 s49, s47, -1
	s_cmp_eq_u32 s84, 40
	s_cselect_b32 s51, s5, s49
	s_cselect_b32 s50, s4, s48
	s_cselect_b32 s49, s45, s83
	s_cselect_b32 s48, s44, s82
	s_add_i32 m0, s59, 0xc000
	ds_read_b128 v[196:199], v164
	ds_read_b128 v[200:203], v164 offset:1024
	ds_read_b128 v[204:207], v164 offset:2048
	ds_read_b128 v[208:211], v164 offset:3072
	ds_read_b128 v[212:215], v164 offset:4096
	ds_read_b128 v[216:219], v164 offset:5120
	ds_read_b128 v[220:223], v164 offset:6144
	ds_read_b128 v[224:227], v164 offset:7168
	global_load_lds_dwordx4 v146, s[46:47]
	s_add_i32 m0, s59, 0xe000
	s_nop 0
	global_load_lds_dwordx4 v148, s[46:47]
	s_waitcnt vmcnt(8)
	s_waitcnt lgkmcnt(0)
	s_setprio 1
	s_barrier
	v_mfma_f32_16x16x32_bf16 v[126:129], v[130:133], v[196:199], v[126:129]
	v_mfma_f32_16x16x32_bf16 v[122:125], v[154:157], v[196:199], v[122:125]
	v_mfma_f32_16x16x32_bf16 v[110:113], v[130:133], v[204:207], v[110:113]
	v_mfma_f32_16x16x32_bf16 v[106:109], v[154:157], v[204:207], v[106:109]
	v_mfma_f32_16x16x32_bf16 v[94:97], v[130:133], v[212:215], v[94:97]
	v_mfma_f32_16x16x32_bf16 v[90:93], v[154:157], v[212:215], v[90:93]
	v_mfma_f32_16x16x32_bf16 v[78:81], v[130:133], v[220:223], v[78:81]
	v_mfma_f32_16x16x32_bf16 v[74:77], v[154:157], v[220:223], v[74:77]
	v_mfma_f32_16x16x32_bf16 v[126:129], v[134:137], v[200:203], v[126:129]
	v_mfma_f32_16x16x32_bf16 v[122:125], v[166:169], v[200:203], v[122:125]
	v_mfma_f32_16x16x32_bf16 v[110:113], v[134:137], v[208:211], v[110:113]
	v_mfma_f32_16x16x32_bf16 v[106:109], v[166:169], v[208:211], v[106:109]
	v_mfma_f32_16x16x32_bf16 v[94:97], v[134:137], v[216:219], v[94:97]
	v_mfma_f32_16x16x32_bf16 v[90:93], v[166:169], v[216:219], v[90:93]
	v_mfma_f32_16x16x32_bf16 v[78:81], v[134:137], v[224:227], v[78:81]
	v_mfma_f32_16x16x32_bf16 v[74:77], v[166:169], v[224:227], v[74:77]
	v_mfma_f32_16x16x32_bf16 v[118:121], v[174:177], v[196:199], v[118:121]
	v_mfma_f32_16x16x32_bf16 v[114:117], v[182:185], v[196:199], v[114:117]
	v_mfma_f32_16x16x32_bf16 v[102:105], v[174:177], v[204:207], v[102:105]
	v_mfma_f32_16x16x32_bf16 v[98:101], v[182:185], v[204:207], v[98:101]
	v_mfma_f32_16x16x32_bf16 v[86:89], v[174:177], v[212:215], v[86:89]
	v_mfma_f32_16x16x32_bf16 v[82:85], v[182:185], v[212:215], v[82:85]
	v_mfma_f32_16x16x32_bf16 v[70:73], v[174:177], v[220:223], v[70:73]
	v_mfma_f32_16x16x32_bf16 v[66:69], v[182:185], v[220:223], v[66:69]
	v_mfma_f32_16x16x32_bf16 v[118:121], v[178:181], v[200:203], v[118:121]
	v_mfma_f32_16x16x32_bf16 v[114:117], v[186:189], v[200:203], v[114:117]
	v_mfma_f32_16x16x32_bf16 v[102:105], v[178:181], v[208:211], v[102:105]
	v_mfma_f32_16x16x32_bf16 v[98:101], v[186:189], v[208:211], v[98:101]
	v_mfma_f32_16x16x32_bf16 v[86:89], v[178:181], v[216:219], v[86:89]
	v_mfma_f32_16x16x32_bf16 v[82:85], v[186:189], v[216:219], v[82:85]
	v_mfma_f32_16x16x32_bf16 v[70:73], v[178:181], v[224:227], v[70:73]
	v_mfma_f32_16x16x32_bf16 v[66:69], v[186:189], v[224:227], v[66:69]
	s_barrier
	s_setprio 0
	s_add_u32 s98, s48, s38
	s_addc_u32 s99, s49, s39
	s_add_u32 s100, s50, s38
	s_addc_u32 s101, s51, s39
	s_add_i32 s85, s76, s58
	s_mov_b32 m0, s85
	ds_read_b128 v[196:199], v164 offset:16384
	ds_read_b128 v[200:203], v164 offset:17408
	ds_read_b128 v[204:207], v164 offset:18432
	ds_read_b128 v[208:211], v164 offset:19456
	ds_read_b128 v[212:215], v164 offset:20480
	ds_read_b128 v[216:219], v164 offset:21504
	ds_read_b128 v[220:223], v164 offset:22528
	ds_read_b128 v[224:227], v164 offset:23552
	global_load_lds_dwordx4 v140, s[48:49]
	s_add_i32 m0, s85, 0x2000
	s_add_u32 s86, s48, 0xb0000
	s_addc_u32 s87, s49, 0
	s_add_i32 s85, s77, s58
	global_load_lds_dwordx4 v144, s[48:49]
	s_mov_b32 m0, s85
	s_nop 0
	global_load_lds_dwordx4 v140, s[86:87]
	s_add_i32 m0, s85, 0x2000
	s_nop 0
	global_load_lds_dwordx4 v144, s[86:87]
	s_mov_b32 m0, s59
	s_nop 0
	global_load_lds_dwordx4 v138, s[50:51]
	s_mov_b32 m0, s60
	s_nop 0
	global_load_lds_dwordx4 v142, s[50:51]
	s_waitcnt vmcnt(8)
	s_waitcnt lgkmcnt(0)
	s_setprio 1
	s_barrier
	v_mfma_f32_16x16x32_bf16 v[62:65], v[130:133], v[196:199], v[62:65]
	v_mfma_f32_16x16x32_bf16 v[58:61], v[154:157], v[196:199], v[58:61]
	v_mfma_f32_16x16x32_bf16 v[46:49], v[130:133], v[204:207], v[46:49]
	v_mfma_f32_16x16x32_bf16 v[42:45], v[154:157], v[204:207], v[42:45]
	v_mfma_f32_16x16x32_bf16 v[30:33], v[130:133], v[212:215], v[30:33]
	v_mfma_f32_16x16x32_bf16 v[26:29], v[154:157], v[212:215], v[26:29]
	v_mfma_f32_16x16x32_bf16 v[14:17], v[130:133], v[220:223], v[14:17]
	v_mfma_f32_16x16x32_bf16 v[10:13], v[154:157], v[220:223], v[10:13]
	v_mfma_f32_16x16x32_bf16 v[62:65], v[134:137], v[200:203], v[62:65]
	v_mfma_f32_16x16x32_bf16 v[58:61], v[166:169], v[200:203], v[58:61]
	v_mfma_f32_16x16x32_bf16 v[46:49], v[134:137], v[208:211], v[46:49]
	v_mfma_f32_16x16x32_bf16 v[42:45], v[166:169], v[208:211], v[42:45]
	v_mfma_f32_16x16x32_bf16 v[30:33], v[134:137], v[216:219], v[30:33]
	v_mfma_f32_16x16x32_bf16 v[26:29], v[166:169], v[216:219], v[26:29]
	v_mfma_f32_16x16x32_bf16 v[14:17], v[134:137], v[224:227], v[14:17]
	v_mfma_f32_16x16x32_bf16 v[10:13], v[166:169], v[224:227], v[10:13]
	v_mfma_f32_16x16x32_bf16 v[54:57], v[174:177], v[196:199], v[54:57]
	v_mfma_f32_16x16x32_bf16 v[50:53], v[182:185], v[196:199], v[50:53]
	v_mfma_f32_16x16x32_bf16 v[38:41], v[174:177], v[204:207], v[38:41]
	v_mfma_f32_16x16x32_bf16 v[34:37], v[182:185], v[204:207], v[34:37]
	v_mfma_f32_16x16x32_bf16 v[22:25], v[174:177], v[212:215], v[22:25]
	v_mfma_f32_16x16x32_bf16 v[18:21], v[182:185], v[212:215], v[18:21]
	v_mfma_f32_16x16x32_bf16 v[6:9], v[174:177], v[220:223], v[6:9]
	v_mfma_f32_16x16x32_bf16 v[2:5], v[182:185], v[220:223], v[2:5]
	v_mfma_f32_16x16x32_bf16 v[54:57], v[178:181], v[200:203], v[54:57]
	v_mfma_f32_16x16x32_bf16 v[50:53], v[186:189], v[200:203], v[50:53]
	v_mfma_f32_16x16x32_bf16 v[38:41], v[178:181], v[208:211], v[38:41]
	v_mfma_f32_16x16x32_bf16 v[34:37], v[186:189], v[208:211], v[34:37]
	v_mfma_f32_16x16x32_bf16 v[22:25], v[178:181], v[216:219], v[22:25]
	v_mfma_f32_16x16x32_bf16 v[18:21], v[186:189], v[216:219], v[18:21]
	v_mfma_f32_16x16x32_bf16 v[6:9], v[178:181], v[224:227], v[6:9]
	v_mfma_f32_16x16x32_bf16 v[2:5], v[186:189], v[224:227], v[2:5]
	s_barrier
; #define PG8_STAGE(bufoff, gbase, voff) do { _Pragma("unroll") for (int _i = 0; _i < 2; ++_i) \
;         __builtin_amdgcn_global_load_lds((const unsigned*)((const char*)(gbase) + (voff)[_i]), (LAS unsigned*)(lds + (bufoff) + ldsw + _i * 8192), 16, 0, 0); } while (0)
; #define PG8_LDA(dst, b, h) do { _Pragma("unroll") for (int m = 0; m < 4; ++m) _Pragma("unroll") for (int k = 0; k < 2; ++k) dst[m][k] = *(const LAS bf16x8*)(lds + PG8_SA(b, h) + aoff + m * 2048 + k * 1024); } while (0)
; #define PG8_LDB(dst, b, h) do { _Pragma("unroll") for (int n = 0; n < 2; ++n) _Pragma("unroll") for (int k = 0; k < 2; ++k) dst[n][k] = *(const LAS bf16x8*)(lds + PG8_SB(b, h) + boff + n * 2048 + k * 1024); } while (0)
; #define PG8_MMA(ai, bj, At, Bt) do { __builtin_amdgcn_s_setprio(1); _Pragma("unroll") for (int m = 0; m < 4; ++m) _Pragma("unroll") for (int n = 0; n < 2; ++n) _Pragma("unroll") for (int k = 0; k < 2; ++k) \
;         acc[ai][bj][m][n] = __builtin_amdgcn_mfma_f32_16x16x32_bf16(Bt[n][k], At[m][k], acc[ai][bj][m][n], 0, 0, 0); __builtin_amdgcn_s_setprio(0); } while (0)
; #define PG8_WAIT_V(n) asm volatile("s_waitcnt vmcnt(" #n ")" ::: "memory")
; #define PG8_WAIT_L(n) asm volatile("s_waitcnt lgkmcnt(" #n ")" ::: "memory")
; #define PG8_BAR __builtin_amdgcn_s_barrier()
; #define PG8_SCHED __builtin_amdgcn_sched_barrier(0)
; template <class Epi>
; __device__ __forceinline__ void gemm_phase(LAS unsigned char* lds, const Gemm g, const StaticOrder& S, const Epi& E) {
;     ...
;         for (int t = 0; t < nt; t += 2) {
;     ...
;             PG8_LDB(B0, 1, 0); PG8_LDB(B1, 1, 1); PG8_SCHED; PG8_LDA(At, 1, 0); PG8_STAGE(PG8_SA(0, 1), a2 + hstep, voffA);
;             PG8_WAIT_V(8); PG8_WAIT_L(0); PG8_BAR; PG8_MMA(0, 0, At, B0); PG8_MMA(0, 1, At, B1); PG8_BAR; PG8_SCHED;
;             PG8_LDA(At, 1, 1); PG8_STAGE(PG8_SB(1, 0), b3, voffB); PG8_STAGE(PG8_SB(1, 1), b3 + hstep, voffB); PG8_STAGE(PG8_SA(1, 0), a3, voffA);
;             PG8_WAIT_V(8); PG8_WAIT_L(0); PG8_BAR; PG8_MMA(1, 0, At, B0); PG8_MMA(1, 1, At, B1); PG8_BAR; PG8_SCHED;
;         }
;         if (wr == 0) PG8_BAR;
	s_setprio 0
	s_add_i32 s85, 0, 0x18000
	s_add_i32 s86, 0, 0x1c000
	v_add_u32_e32 v166, s85, v160
	v_add_u32_e32 v186, s86, v160
	ds_read_b128 v[130:133], v166
	ds_read_b128 v[134:137], v166 offset:1024
	ds_read_b128 v[154:157], v166 offset:2048
	ds_read_b128 v[166:169], v166 offset:3072
	ds_read_b128 v[174:177], v186
	ds_read_b128 v[178:181], v186 offset:1024
	ds_read_b128 v[182:185], v186 offset:2048
	ds_read_b128 v[186:189], v186 offset:3072
	s_add_u32 s50, s50, 0xb0000
	s_addc_u32 s51, s51, 0
	s_mov_b32 m0, s61
	ds_read_b128 v[196:199], v164 offset:32768
	ds_read_b128 v[200:203], v164 offset:33792
	ds_read_b128 v[204:207], v164 offset:34816
	ds_read_b128 v[208:211], v164 offset:35840
	ds_read_b128 v[212:215], v164 offset:36864
	ds_read_b128 v[216:219], v164 offset:37888
	ds_read_b128 v[220:223], v164 offset:38912
	ds_read_b128 v[224:227], v164 offset:39936
	global_load_lds_dwordx4 v138, s[50:51]
	s_mov_b32 m0, s62
	s_nop 0
	global_load_lds_dwordx4 v142, s[50:51]
	s_waitcnt vmcnt(8)
	s_waitcnt lgkmcnt(0)
	s_setprio 1
	s_barrier
	v_mfma_f32_16x16x32_bf16 v[126:129], v[130:133], v[196:199], v[126:129]
	v_mfma_f32_16x16x32_bf16 v[122:125], v[154:157], v[196:199], v[122:125]
	v_mfma_f32_16x16x32_bf16 v[110:113], v[130:133], v[204:207], v[110:113]
	v_mfma_f32_16x16x32_bf16 v[106:109], v[154:157], v[204:207], v[106:109]
	v_mfma_f32_16x16x32_bf16 v[94:97], v[130:133], v[212:215], v[94:97]
	v_mfma_f32_16x16x32_bf16 v[90:93], v[154:157], v[212:215], v[90:93]
	v_mfma_f32_16x16x32_bf16 v[78:81], v[130:133], v[220:223], v[78:81]
	v_mfma_f32_16x16x32_bf16 v[74:77], v[154:157], v[220:223], v[74:77]
	v_mfma_f32_16x16x32_bf16 v[126:129], v[134:137], v[200:203], v[126:129]
	v_mfma_f32_16x16x32_bf16 v[122:125], v[166:169], v[200:203], v[122:125]
	v_mfma_f32_16x16x32_bf16 v[110:113], v[134:137], v[208:211], v[110:113]
	v_mfma_f32_16x16x32_bf16 v[106:109], v[166:169], v[208:211], v[106:109]
	v_mfma_f32_16x16x32_bf16 v[94:97], v[134:137], v[216:219], v[94:97]
	v_mfma_f32_16x16x32_bf16 v[90:93], v[166:169], v[216:219], v[90:93]
	v_mfma_f32_16x16x32_bf16 v[78:81], v[134:137], v[224:227], v[78:81]
	v_mfma_f32_16x16x32_bf16 v[74:77], v[166:169], v[224:227], v[74:77]
	v_mfma_f32_16x16x32_bf16 v[118:121], v[174:177], v[196:199], v[118:121]
	v_mfma_f32_16x16x32_bf16 v[114:117], v[182:185], v[196:199], v[114:117]
	v_mfma_f32_16x16x32_bf16 v[102:105], v[174:177], v[204:207], v[102:105]
	v_mfma_f32_16x16x32_bf16 v[98:101], v[182:185], v[204:207], v[98:101]
	v_mfma_f32_16x16x32_bf16 v[86:89], v[174:177], v[212:215], v[86:89]
	v_mfma_f32_16x16x32_bf16 v[82:85], v[182:185], v[212:215], v[82:85]
	v_mfma_f32_16x16x32_bf16 v[70:73], v[174:177], v[220:223], v[70:73]
	v_mfma_f32_16x16x32_bf16 v[66:69], v[182:185], v[220:223], v[66:69]
	v_mfma_f32_16x16x32_bf16 v[118:121], v[178:181], v[200:203], v[118:121]
	v_mfma_f32_16x16x32_bf16 v[114:117], v[186:189], v[200:203], v[114:117]
	v_mfma_f32_16x16x32_bf16 v[102:105], v[178:181], v[208:211], v[102:105]
	v_mfma_f32_16x16x32_bf16 v[98:101], v[186:189], v[208:211], v[98:101]
	v_mfma_f32_16x16x32_bf16 v[86:89], v[178:181], v[216:219], v[86:89]
	v_mfma_f32_16x16x32_bf16 v[82:85], v[186:189], v[216:219], v[82:85]
	v_mfma_f32_16x16x32_bf16 v[70:73], v[178:181], v[224:227], v[70:73]
	v_mfma_f32_16x16x32_bf16 v[66:69], v[186:189], v[224:227], v[66:69]
	s_barrier
	s_setprio 0
	s_add_i32 s50, s85, s58
	s_mov_b32 m0, s50
	ds_read_b128 v[196:199], v164 offset:49152
	ds_read_b128 v[200:203], v164 offset:50176
	ds_read_b128 v[204:207], v164 offset:51200
	ds_read_b128 v[208:211], v164 offset:52224
	ds_read_b128 v[212:215], v164 offset:53248
	ds_read_b128 v[216:219], v164 offset:54272
	ds_read_b128 v[220:223], v164 offset:55296
	ds_read_b128 v[224:227], v164 offset:56320
	global_load_lds_dwordx4 v140, s[98:99]
	s_add_i32 m0, s50, 0x2000
	s_add_u32 s48, s48, 0xb0080
	s_addc_u32 s49, s49, 0
	s_add_i32 s50, s86, s58
	global_load_lds_dwordx4 v144, s[98:99]
	s_mov_b32 m0, s50
	s_nop 0
	global_load_lds_dwordx4 v140, s[48:49]
	s_add_i32 m0, s50, 0x2000
	s_nop 0
	global_load_lds_dwordx4 v144, s[48:49]
	s_mov_b32 m0, s64
	s_nop 0
	global_load_lds_dwordx4 v138, s[100:101]
	s_mov_b32 m0, s65
	s_nop 0
	global_load_lds_dwordx4 v142, s[100:101]
	s_waitcnt vmcnt(8)
	s_waitcnt lgkmcnt(0)
	s_setprio 1
	s_barrier
	v_mfma_f32_16x16x32_bf16 v[62:65], v[130:133], v[196:199], v[62:65]
	v_mfma_f32_16x16x32_bf16 v[58:61], v[154:157], v[196:199], v[58:61]
	v_mfma_f32_16x16x32_bf16 v[46:49], v[130:133], v[204:207], v[46:49]
	v_mfma_f32_16x16x32_bf16 v[42:45], v[154:157], v[204:207], v[42:45]
	v_mfma_f32_16x16x32_bf16 v[30:33], v[130:133], v[212:215], v[30:33]
	v_mfma_f32_16x16x32_bf16 v[26:29], v[154:157], v[212:215], v[26:29]
	v_mfma_f32_16x16x32_bf16 v[14:17], v[130:133], v[220:223], v[14:17]
	v_mfma_f32_16x16x32_bf16 v[10:13], v[154:157], v[220:223], v[10:13]
	v_mfma_f32_16x16x32_bf16 v[62:65], v[134:137], v[200:203], v[62:65]
	v_mfma_f32_16x16x32_bf16 v[58:61], v[166:169], v[200:203], v[58:61]
	v_mfma_f32_16x16x32_bf16 v[46:49], v[134:137], v[208:211], v[46:49]
	v_mfma_f32_16x16x32_bf16 v[42:45], v[166:169], v[208:211], v[42:45]
	v_mfma_f32_16x16x32_bf16 v[30:33], v[134:137], v[216:219], v[30:33]
	v_mfma_f32_16x16x32_bf16 v[26:29], v[166:169], v[216:219], v[26:29]
	v_mfma_f32_16x16x32_bf16 v[14:17], v[134:137], v[224:227], v[14:17]
	v_mfma_f32_16x16x32_bf16 v[10:13], v[166:169], v[224:227], v[10:13]
	v_mfma_f32_16x16x32_bf16 v[54:57], v[174:177], v[196:199], v[54:57]
	v_mfma_f32_16x16x32_bf16 v[50:53], v[182:185], v[196:199], v[50:53]
	v_mfma_f32_16x16x32_bf16 v[38:41], v[174:177], v[204:207], v[38:41]
	v_mfma_f32_16x16x32_bf16 v[34:37], v[182:185], v[204:207], v[34:37]
	v_mfma_f32_16x16x32_bf16 v[22:25], v[174:177], v[212:215], v[22:25]
	v_mfma_f32_16x16x32_bf16 v[18:21], v[182:185], v[212:215], v[18:21]
	v_mfma_f32_16x16x32_bf16 v[6:9], v[174:177], v[220:223], v[6:9]
	v_mfma_f32_16x16x32_bf16 v[2:5], v[182:185], v[220:223], v[2:5]
	v_mfma_f32_16x16x32_bf16 v[54:57], v[178:181], v[200:203], v[54:57]
	v_mfma_f32_16x16x32_bf16 v[50:53], v[186:189], v[200:203], v[50:53]
	v_mfma_f32_16x16x32_bf16 v[38:41], v[178:181], v[208:211], v[38:41]
	v_mfma_f32_16x16x32_bf16 v[34:37], v[186:189], v[208:211], v[34:37]
	v_mfma_f32_16x16x32_bf16 v[22:25], v[178:181], v[216:219], v[22:25]
	v_mfma_f32_16x16x32_bf16 v[18:21], v[186:189], v[216:219], v[18:21]
	v_mfma_f32_16x16x32_bf16 v[6:9], v[178:181], v[224:227], v[6:9]
	v_mfma_f32_16x16x32_bf16 v[2:5], v[186:189], v[224:227], v[2:5]
	s_barrier
	s_setprio 0
	s_add_i32 s84, s84, 2
	s_add_u32 s46, s46, 0x100
	s_addc_u32 s47, s47, 0
	s_add_u32 s82, s82, 0x100
	s_addc_u32 s83, s83, 0
	s_cmp_gt_u32 s84, 41
	s_cbranch_scc0 .LBB0_221
	s_and_b64 vcc, exec, s[42:43]
	s_cbranch_vccz .LBB0_224
	s_barrier

; #define PG8_STAGE(bufoff, gbase, voff) do { _Pragma("unroll") for (int _i = 0; _i < 2; ++_i) \
;         __builtin_amdgcn_global_load_lds((const unsigned*)((const char*)(gbase) + (voff)[_i]), (LAS unsigned*)(lds + (bufoff) + ldsw + _i * 8192), 16, 0, 0); } while (0)
; #define PG8_LDA(dst, b, h) do { _Pragma("unroll") for (int m = 0; m < 4; ++m) _Pragma("unroll") for (int k = 0; k < 2; ++k) dst[m][k] = *(const LAS bf16x8*)(lds + PG8_SA(b, h) + aoff + m * 2048 + k * 1024); } while (0)
; #define PG8_LDB(dst, b, h) do { _Pragma("unroll") for (int n = 0; n < 2; ++n) _Pragma("unroll") for (int k = 0; k < 2; ++k) dst[n][k] = *(const LAS bf16x8*)(lds + PG8_SB(b, h) + boff + n * 2048 + k * 1024); } while (0)
; #define PG8_MMA(ai, bj, At, Bt) do { __builtin_amdgcn_s_setprio(1); _Pragma("unroll") for (int m = 0; m < 4; ++m) _Pragma("unroll") for (int n = 0; n < 2; ++n) _Pragma("unroll") for (int k = 0; k < 2; ++k) \
;         acc[ai][bj][m][n] = __builtin_amdgcn_mfma_f32_16x16x32_bf16(Bt[n][k], At[m][k], acc[ai][bj][m][n], 0, 0, 0); __builtin_amdgcn_s_setprio(0); } while (0)
; #define PG8_WAIT_V(n) asm volatile("s_waitcnt vmcnt(" #n ")" ::: "memory")
; #define PG8_WAIT_L(n) asm volatile("s_waitcnt lgkmcnt(" #n ")" ::: "memory")
; #define PG8_BAR __builtin_amdgcn_s_barrier()
; template <class Epi>
; __device__ __forceinline__ void gemm_phase(LAS unsigned char* lds, const Gemm g, const StaticOrder& S, const Epi& E) {
;     ...
;         for (int t = 0; t < nt; t += 2) {
;             const bool last = (t == nt - 2);
;             const char* a1 = cA + (size_t)(t + 1) * kstep;
;             const char* a2 = last ? nA : cA + (size_t)(t + 2) * kstep; const char* b2 = last ? nB : cB + (size_t)(t + 2) * kstep;
;             const char* a3 = a2 + kstep; const char* b3 = b2 + kstep;
;             if constexpr (Epi::MIDK > 0) { if (t == Epi::MIDK) E.mid(acc, cur, wr, wc, fr, fq); }
;             PG8_LDB(B0, 0, 0); PG8_LDB(B1, 0, 1); PG8_SCHED; PG8_LDA(At, 0, 0); PG8_STAGE(PG8_SA(1, 1), a1 + hstep, voffA);
;             PG8_WAIT_V(8); PG8_WAIT_L(0); PG8_BAR; PG8_MMA(0, 0, At, B0); PG8_MMA(0, 1, At, B1); PG8_BAR; PG8_SCHED;
;             PG8_LDA(At, 0, 1); PG8_STAGE(PG8_SB(0, 0), b2, voffB); PG8_STAGE(PG8_SB(0, 1), b2 + hstep, voffB); PG8_STAGE(PG8_SA(0, 0), a2, voffA);
;             PG8_WAIT_V(8); PG8_WAIT_L(0); PG8_BAR; PG8_MMA(1, 0, At, B0); PG8_MMA(1, 1, At, B1); PG8_BAR; PG8_SCHED;
.LBB0_322:
	ds_read_b128 v[130:133], v191
	ds_read_b128 v[134:137], v191 offset:1024
	ds_read_b128 v[138:141], v191 offset:2048
	ds_read_b128 v[142:145], v191 offset:3072
	ds_read_b128 v[166:169], v193
	ds_read_b128 v[174:177], v193 offset:1024
	ds_read_b128 v[178:181], v193 offset:2048
	ds_read_b128 v[182:185], v193 offset:3072
	s_add_u32 s76, s88, 0xfffc0080
	s_addc_u32 s77, s89, -1
	s_cmp_eq_u32 vcc_hi, 12
	s_cselect_b32 s93, s1, s77
	s_cselect_b32 s92, s7, s76
	s_cselect_b32 s91, s9, vcc_lo
	s_cselect_b32 s90, s46, s81
	s_add_i32 m0, s96, 0xc000
	ds_read_b128 v[208:211], v194
	ds_read_b128 v[212:215], v194 offset:1024
	ds_read_b128 v[216:219], v194 offset:2048
	ds_read_b128 v[220:223], v194 offset:3072
	ds_read_b128 v[224:227], v194 offset:4096
	ds_read_b128 v[228:231], v194 offset:5120
	ds_read_b128 v[232:235], v194 offset:6144
	ds_read_b128 v[236:239], v194 offset:7168
	global_load_lds_dwordx4 v158, s[88:89]
	s_add_i32 m0, s96, 0xe000
	s_nop 0
	global_load_lds_dwordx4 v160, s[88:89]
	s_waitcnt vmcnt(8)
	s_waitcnt lgkmcnt(0)
	s_setprio 1
	s_barrier
	v_mfma_f32_16x16x32_bf16 v[126:129], v[130:133], v[208:211], v[126:129]
	v_mfma_f32_16x16x32_bf16 v[122:125], v[138:141], v[208:211], v[122:125]
	v_mfma_f32_16x16x32_bf16 v[110:113], v[130:133], v[216:219], v[110:113]
	v_mfma_f32_16x16x32_bf16 v[106:109], v[138:141], v[216:219], v[106:109]
	v_mfma_f32_16x16x32_bf16 v[94:97], v[130:133], v[224:227], v[94:97]
	v_mfma_f32_16x16x32_bf16 v[90:93], v[138:141], v[224:227], v[90:93]
	v_mfma_f32_16x16x32_bf16 v[78:81], v[130:133], v[232:235], v[78:81]
	v_mfma_f32_16x16x32_bf16 v[74:77], v[138:141], v[232:235], v[74:77]
	v_mfma_f32_16x16x32_bf16 v[126:129], v[134:137], v[212:215], v[126:129]
	v_mfma_f32_16x16x32_bf16 v[122:125], v[142:145], v[212:215], v[122:125]
	v_mfma_f32_16x16x32_bf16 v[110:113], v[134:137], v[220:223], v[110:113]
	v_mfma_f32_16x16x32_bf16 v[106:109], v[142:145], v[220:223], v[106:109]
	v_mfma_f32_16x16x32_bf16 v[94:97], v[134:137], v[228:231], v[94:97]
	v_mfma_f32_16x16x32_bf16 v[90:93], v[142:145], v[228:231], v[90:93]
	v_mfma_f32_16x16x32_bf16 v[78:81], v[134:137], v[236:239], v[78:81]
	v_mfma_f32_16x16x32_bf16 v[74:77], v[142:145], v[236:239], v[74:77]
	v_mfma_f32_16x16x32_bf16 v[118:121], v[166:169], v[208:211], v[118:121]
	v_mfma_f32_16x16x32_bf16 v[114:117], v[178:181], v[208:211], v[114:117]
	v_mfma_f32_16x16x32_bf16 v[102:105], v[166:169], v[216:219], v[102:105]
	v_mfma_f32_16x16x32_bf16 v[98:101], v[178:181], v[216:219], v[98:101]
	v_mfma_f32_16x16x32_bf16 v[86:89], v[166:169], v[224:227], v[86:89]
	v_mfma_f32_16x16x32_bf16 v[82:85], v[178:181], v[224:227], v[82:85]
	v_mfma_f32_16x16x32_bf16 v[70:73], v[166:169], v[232:235], v[70:73]
	v_mfma_f32_16x16x32_bf16 v[66:69], v[178:181], v[232:235], v[66:69]
	v_mfma_f32_16x16x32_bf16 v[118:121], v[174:177], v[212:215], v[118:121]
	v_mfma_f32_16x16x32_bf16 v[114:117], v[182:185], v[212:215], v[114:117]
	v_mfma_f32_16x16x32_bf16 v[102:105], v[174:177], v[220:223], v[102:105]
	v_mfma_f32_16x16x32_bf16 v[98:101], v[182:185], v[220:223], v[98:101]
	v_mfma_f32_16x16x32_bf16 v[86:89], v[174:177], v[228:231], v[86:89]
	v_mfma_f32_16x16x32_bf16 v[82:85], v[182:185], v[228:231], v[82:85]
	v_mfma_f32_16x16x32_bf16 v[70:73], v[174:177], v[236:239], v[70:73]
	v_mfma_f32_16x16x32_bf16 v[66:69], v[182:185], v[236:239], v[66:69]
	s_barrier
	s_setprio 0
	s_add_u32 s98, s90, s50
	s_addc_u32 s99, s91, s51
	s_add_u32 s100, s92, s50
	s_addc_u32 s101, s93, s51
	s_add_i32 s76, s42, s44
	s_mov_b32 m0, s76
	ds_read_b128 v[208:211], v194 offset:16384
	ds_read_b128 v[212:215], v194 offset:17408
	ds_read_b128 v[216:219], v194 offset:18432
	ds_read_b128 v[220:223], v194 offset:19456
	ds_read_b128 v[224:227], v194 offset:20480
	ds_read_b128 v[228:231], v194 offset:21504
	ds_read_b128 v[232:235], v194 offset:22528
	ds_read_b128 v[236:239], v194 offset:23552
	global_load_lds_dwordx4 v148, s[90:91]
	s_add_i32 m0, s76, 0x2000
	s_add_u32 s76, s90, 0x40000
	s_addc_u32 s77, s91, 0
	s_add_i32 s60, s43, s44
	global_load_lds_dwordx4 v152, s[90:91]
	s_mov_b32 m0, s60
	s_nop 0
	global_load_lds_dwordx4 v148, s[76:77]
	s_add_i32 m0, s60, 0x2000
	s_nop 0
	global_load_lds_dwordx4 v152, s[76:77]
	s_mov_b32 m0, s96
	s_nop 0
	global_load_lds_dwordx4 v146, s[92:93]
	s_mov_b32 m0, s97
	s_nop 0
	global_load_lds_dwordx4 v150, s[92:93]
	s_waitcnt vmcnt(8)
	s_waitcnt lgkmcnt(0)
	s_setprio 1
	s_barrier
	v_mfma_f32_16x16x32_bf16 v[62:65], v[130:133], v[208:211], v[62:65]
	v_mfma_f32_16x16x32_bf16 v[58:61], v[138:141], v[208:211], v[58:61]
	v_mfma_f32_16x16x32_bf16 v[46:49], v[130:133], v[216:219], v[46:49]
	v_mfma_f32_16x16x32_bf16 v[42:45], v[138:141], v[216:219], v[42:45]
	v_mfma_f32_16x16x32_bf16 v[30:33], v[130:133], v[224:227], v[30:33]
	v_mfma_f32_16x16x32_bf16 v[26:29], v[138:141], v[224:227], v[26:29]
	v_mfma_f32_16x16x32_bf16 v[14:17], v[130:133], v[232:235], v[14:17]
	v_mfma_f32_16x16x32_bf16 v[10:13], v[138:141], v[232:235], v[10:13]
	v_mfma_f32_16x16x32_bf16 v[62:65], v[134:137], v[212:215], v[62:65]
	v_mfma_f32_16x16x32_bf16 v[58:61], v[142:145], v[212:215], v[58:61]
	v_mfma_f32_16x16x32_bf16 v[46:49], v[134:137], v[220:223], v[46:49]
	v_mfma_f32_16x16x32_bf16 v[42:45], v[142:145], v[220:223], v[42:45]
	v_mfma_f32_16x16x32_bf16 v[30:33], v[134:137], v[228:231], v[30:33]
	v_mfma_f32_16x16x32_bf16 v[26:29], v[142:145], v[228:231], v[26:29]
	v_mfma_f32_16x16x32_bf16 v[14:17], v[134:137], v[236:239], v[14:17]
	v_mfma_f32_16x16x32_bf16 v[10:13], v[142:145], v[236:239], v[10:13]
	v_mfma_f32_16x16x32_bf16 v[54:57], v[166:169], v[208:211], v[54:57]
	v_mfma_f32_16x16x32_bf16 v[50:53], v[178:181], v[208:211], v[50:53]
	v_mfma_f32_16x16x32_bf16 v[38:41], v[166:169], v[216:219], v[38:41]
	v_mfma_f32_16x16x32_bf16 v[34:37], v[178:181], v[216:219], v[34:37]
	v_mfma_f32_16x16x32_bf16 v[22:25], v[166:169], v[224:227], v[22:25]
	v_mfma_f32_16x16x32_bf16 v[18:21], v[178:181], v[224:227], v[18:21]
	v_mfma_f32_16x16x32_bf16 v[6:9], v[166:169], v[232:235], v[6:9]
	v_mfma_f32_16x16x32_bf16 v[2:5], v[178:181], v[232:235], v[2:5]
	v_mfma_f32_16x16x32_bf16 v[54:57], v[174:177], v[212:215], v[54:57]
	v_mfma_f32_16x16x32_bf16 v[50:53], v[182:185], v[212:215], v[50:53]
	v_mfma_f32_16x16x32_bf16 v[38:41], v[174:177], v[220:223], v[38:41]
	v_mfma_f32_16x16x32_bf16 v[34:37], v[182:185], v[220:223], v[34:37]
	v_mfma_f32_16x16x32_bf16 v[22:25], v[174:177], v[228:231], v[22:25]
	v_mfma_f32_16x16x32_bf16 v[18:21], v[182:185], v[228:231], v[18:21]
	v_mfma_f32_16x16x32_bf16 v[6:9], v[174:177], v[236:239], v[6:9]
	v_mfma_f32_16x16x32_bf16 v[2:5], v[182:185], v[236:239], v[2:5]
	s_barrier
; #define PG8_STAGE(bufoff, gbase, voff) do { _Pragma("unroll") for (int _i = 0; _i < 2; ++_i) \
;         __builtin_amdgcn_global_load_lds((const unsigned*)((const char*)(gbase) + (voff)[_i]), (LAS unsigned*)(lds + (bufoff) + ldsw + _i * 8192), 16, 0, 0); } while (0)
; #define PG8_LDA(dst, b, h) do { _Pragma("unroll") for (int m = 0; m < 4; ++m) _Pragma("unroll") for (int k = 0; k < 2; ++k) dst[m][k] = *(const LAS bf16x8*)(lds + PG8_SA(b, h) + aoff + m * 2048 + k * 1024); } while (0)
; #define PG8_LDB(dst, b, h) do { _Pragma("unroll") for (int n = 0; n < 2; ++n) _Pragma("unroll") for (int k = 0; k < 2; ++k) dst[n][k] = *(const LAS bf16x8*)(lds + PG8_SB(b, h) + boff + n * 2048 + k * 1024); } while (0)
; #define PG8_MMA(ai, bj, At, Bt) do { __builtin_amdgcn_s_setprio(1); _Pragma("unroll") for (int m = 0; m < 4; ++m) _Pragma("unroll") for (int n = 0; n < 2; ++n) _Pragma("unroll") for (int k = 0; k < 2; ++k) \
;         acc[ai][bj][m][n] = __builtin_amdgcn_mfma_f32_16x16x32_bf16(Bt[n][k], At[m][k], acc[ai][bj][m][n], 0, 0, 0); __builtin_amdgcn_s_setprio(0); } while (0)
; #define PG8_WAIT_V(n) asm volatile("s_waitcnt vmcnt(" #n ")" ::: "memory")
; #define PG8_WAIT_L(n) asm volatile("s_waitcnt lgkmcnt(" #n ")" ::: "memory")
; #define PG8_BAR __builtin_amdgcn_s_barrier()
; #define PG8_SCHED __builtin_amdgcn_sched_barrier(0)
; template <class Epi>
; __device__ __forceinline__ void gemm_phase(LAS unsigned char* lds, const Gemm g, const StaticOrder& S, const Epi& E) {
;     ...
;         for (int t = 0; t < nt; t += 2) {
;     ...
;             PG8_LDB(B0, 1, 0); PG8_LDB(B1, 1, 1); PG8_SCHED; PG8_LDA(At, 1, 0); PG8_STAGE(PG8_SA(0, 1), a2 + hstep, voffA);
;             PG8_WAIT_V(8); PG8_WAIT_L(0); PG8_BAR; PG8_MMA(0, 0, At, B0); PG8_MMA(0, 1, At, B1); PG8_BAR; PG8_SCHED;
;             PG8_LDA(At, 1, 1); PG8_STAGE(PG8_SB(1, 0), b3, voffB); PG8_STAGE(PG8_SB(1, 1), b3 + hstep, voffB); PG8_STAGE(PG8_SA(1, 0), a3, voffA);
;             PG8_WAIT_V(8); PG8_WAIT_L(0); PG8_BAR; PG8_MMA(1, 0, At, B0); PG8_MMA(1, 1, At, B1); PG8_BAR; PG8_SCHED;
;         }
;         if (wr == 0) PG8_BAR;
	s_setprio 0
	s_add_i32 s60, 0, 0x18000
	s_add_i32 s61, 0, 0x1c000
	v_add_u32_e32 v142, s60, v187
	v_add_u32_e32 v182, s61, v187
	ds_read_b128 v[130:133], v142
	ds_read_b128 v[134:137], v142 offset:1024
	ds_read_b128 v[138:141], v142 offset:2048
	ds_read_b128 v[142:145], v142 offset:3072
	ds_read_b128 v[166:169], v182
	ds_read_b128 v[174:177], v182 offset:1024
	ds_read_b128 v[178:181], v182 offset:2048
	ds_read_b128 v[182:185], v182 offset:3072
	s_add_u32 s76, s92, 0x40000
	s_addc_u32 s77, s93, 0
	s_mov_b32 m0, s11
	ds_read_b128 v[208:211], v194 offset:32768
	ds_read_b128 v[212:215], v194 offset:33792
	ds_read_b128 v[216:219], v194 offset:34816
	ds_read_b128 v[220:223], v194 offset:35840
	ds_read_b128 v[224:227], v194 offset:36864
	ds_read_b128 v[228:231], v194 offset:37888
	ds_read_b128 v[232:235], v194 offset:38912
	ds_read_b128 v[236:239], v194 offset:39936
	global_load_lds_dwordx4 v146, s[76:77]
	s_mov_b32 m0, s94
	s_nop 0
	global_load_lds_dwordx4 v150, s[76:77]
	s_waitcnt vmcnt(8)
	s_waitcnt lgkmcnt(0)
	s_setprio 1
	s_barrier
	v_mfma_f32_16x16x32_bf16 v[126:129], v[130:133], v[208:211], v[126:129]
	v_mfma_f32_16x16x32_bf16 v[122:125], v[138:141], v[208:211], v[122:125]
	v_mfma_f32_16x16x32_bf16 v[110:113], v[130:133], v[216:219], v[110:113]
	v_mfma_f32_16x16x32_bf16 v[106:109], v[138:141], v[216:219], v[106:109]
	v_mfma_f32_16x16x32_bf16 v[94:97], v[130:133], v[224:227], v[94:97]
	v_mfma_f32_16x16x32_bf16 v[90:93], v[138:141], v[224:227], v[90:93]
	v_mfma_f32_16x16x32_bf16 v[78:81], v[130:133], v[232:235], v[78:81]
	v_mfma_f32_16x16x32_bf16 v[74:77], v[138:141], v[232:235], v[74:77]
	v_mfma_f32_16x16x32_bf16 v[126:129], v[134:137], v[212:215], v[126:129]
	v_mfma_f32_16x16x32_bf16 v[122:125], v[142:145], v[212:215], v[122:125]
	v_mfma_f32_16x16x32_bf16 v[110:113], v[134:137], v[220:223], v[110:113]
	v_mfma_f32_16x16x32_bf16 v[106:109], v[142:145], v[220:223], v[106:109]
	v_mfma_f32_16x16x32_bf16 v[94:97], v[134:137], v[228:231], v[94:97]
	v_mfma_f32_16x16x32_bf16 v[90:93], v[142:145], v[228:231], v[90:93]
	v_mfma_f32_16x16x32_bf16 v[78:81], v[134:137], v[236:239], v[78:81]
	v_mfma_f32_16x16x32_bf16 v[74:77], v[142:145], v[236:239], v[74:77]
	v_mfma_f32_16x16x32_bf16 v[118:121], v[166:169], v[208:211], v[118:121]
	v_mfma_f32_16x16x32_bf16 v[114:117], v[178:181], v[208:211], v[114:117]
	v_mfma_f32_16x16x32_bf16 v[102:105], v[166:169], v[216:219], v[102:105]
	v_mfma_f32_16x16x32_bf16 v[98:101], v[178:181], v[216:219], v[98:101]
	v_mfma_f32_16x16x32_bf16 v[86:89], v[166:169], v[224:227], v[86:89]
	v_mfma_f32_16x16x32_bf16 v[82:85], v[178:181], v[224:227], v[82:85]
	v_mfma_f32_16x16x32_bf16 v[70:73], v[166:169], v[232:235], v[70:73]
	v_mfma_f32_16x16x32_bf16 v[66:69], v[178:181], v[232:235], v[66:69]
	v_mfma_f32_16x16x32_bf16 v[118:121], v[174:177], v[212:215], v[118:121]
	v_mfma_f32_16x16x32_bf16 v[114:117], v[182:185], v[212:215], v[114:117]
	v_mfma_f32_16x16x32_bf16 v[102:105], v[174:177], v[220:223], v[102:105]
	v_mfma_f32_16x16x32_bf16 v[98:101], v[182:185], v[220:223], v[98:101]
	v_mfma_f32_16x16x32_bf16 v[86:89], v[174:177], v[228:231], v[86:89]
	v_mfma_f32_16x16x32_bf16 v[82:85], v[182:185], v[228:231], v[82:85]
	v_mfma_f32_16x16x32_bf16 v[70:73], v[174:177], v[236:239], v[70:73]
	v_mfma_f32_16x16x32_bf16 v[66:69], v[182:185], v[236:239], v[66:69]
	s_barrier
	s_setprio 0
	s_add_i32 s60, s60, s44
	s_mov_b32 m0, s60
	ds_read_b128 v[208:211], v194 offset:49152
	ds_read_b128 v[212:215], v194 offset:50176
	ds_read_b128 v[216:219], v194 offset:51200
	ds_read_b128 v[220:223], v194 offset:52224
	ds_read_b128 v[224:227], v194 offset:53248
	ds_read_b128 v[228:231], v194 offset:54272
	ds_read_b128 v[232:235], v194 offset:55296
	ds_read_b128 v[236:239], v194 offset:56320
	global_load_lds_dwordx4 v148, s[98:99]
	s_add_i32 m0, s60, 0x2000
	s_add_u32 s76, s90, 0x40080
	s_addc_u32 s77, s91, 0
	s_add_i32 s60, s61, s44
	global_load_lds_dwordx4 v152, s[98:99]
	s_mov_b32 m0, s60
	s_nop 0
	global_load_lds_dwordx4 v148, s[76:77]
	s_add_i32 m0, s60, 0x2000
	s_nop 0
	global_load_lds_dwordx4 v152, s[76:77]
	s_mov_b32 m0, s79
	s_nop 0
	global_load_lds_dwordx4 v146, s[100:101]
	s_mov_b32 m0, s33
	s_nop 0
	global_load_lds_dwordx4 v150, s[100:101]
	s_waitcnt vmcnt(8)
	s_waitcnt lgkmcnt(0)
	s_setprio 1
	s_barrier
	v_mfma_f32_16x16x32_bf16 v[62:65], v[130:133], v[208:211], v[62:65]
	v_mfma_f32_16x16x32_bf16 v[58:61], v[138:141], v[208:211], v[58:61]
	v_mfma_f32_16x16x32_bf16 v[46:49], v[130:133], v[216:219], v[46:49]
	v_mfma_f32_16x16x32_bf16 v[42:45], v[138:141], v[216:219], v[42:45]
	v_mfma_f32_16x16x32_bf16 v[30:33], v[130:133], v[224:227], v[30:33]
	v_mfma_f32_16x16x32_bf16 v[26:29], v[138:141], v[224:227], v[26:29]
	v_mfma_f32_16x16x32_bf16 v[14:17], v[130:133], v[232:235], v[14:17]
	v_mfma_f32_16x16x32_bf16 v[10:13], v[138:141], v[232:235], v[10:13]
	v_mfma_f32_16x16x32_bf16 v[62:65], v[134:137], v[212:215], v[62:65]
	v_mfma_f32_16x16x32_bf16 v[58:61], v[142:145], v[212:215], v[58:61]
	v_mfma_f32_16x16x32_bf16 v[46:49], v[134:137], v[220:223], v[46:49]
	v_mfma_f32_16x16x32_bf16 v[42:45], v[142:145], v[220:223], v[42:45]
	v_mfma_f32_16x16x32_bf16 v[30:33], v[134:137], v[228:231], v[30:33]
	v_mfma_f32_16x16x32_bf16 v[26:29], v[142:145], v[228:231], v[26:29]
	v_mfma_f32_16x16x32_bf16 v[14:17], v[134:137], v[236:239], v[14:17]
	v_mfma_f32_16x16x32_bf16 v[10:13], v[142:145], v[236:239], v[10:13]
	v_mfma_f32_16x16x32_bf16 v[54:57], v[166:169], v[208:211], v[54:57]
	v_mfma_f32_16x16x32_bf16 v[50:53], v[178:181], v[208:211], v[50:53]
	v_mfma_f32_16x16x32_bf16 v[38:41], v[166:169], v[216:219], v[38:41]
	v_mfma_f32_16x16x32_bf16 v[34:37], v[178:181], v[216:219], v[34:37]
	v_mfma_f32_16x16x32_bf16 v[22:25], v[166:169], v[224:227], v[22:25]
	v_mfma_f32_16x16x32_bf16 v[18:21], v[178:181], v[224:227], v[18:21]
	v_mfma_f32_16x16x32_bf16 v[6:9], v[166:169], v[232:235], v[6:9]
	v_mfma_f32_16x16x32_bf16 v[2:5], v[178:181], v[232:235], v[2:5]
	v_mfma_f32_16x16x32_bf16 v[54:57], v[174:177], v[212:215], v[54:57]
	v_mfma_f32_16x16x32_bf16 v[50:53], v[182:185], v[212:215], v[50:53]
	v_mfma_f32_16x16x32_bf16 v[38:41], v[174:177], v[220:223], v[38:41]
	v_mfma_f32_16x16x32_bf16 v[34:37], v[182:185], v[220:223], v[34:37]
	v_mfma_f32_16x16x32_bf16 v[22:25], v[174:177], v[228:231], v[22:25]
	v_mfma_f32_16x16x32_bf16 v[18:21], v[182:185], v[228:231], v[18:21]
	v_mfma_f32_16x16x32_bf16 v[6:9], v[174:177], v[236:239], v[6:9]
	v_mfma_f32_16x16x32_bf16 v[2:5], v[182:185], v[236:239], v[2:5]
	s_barrier
	s_setprio 0
	s_add_i32 vcc_hi, vcc_hi, 2
	s_add_u32 s88, s88, 0x100
	s_addc_u32 s89, s89, 0
	s_add_u32 s81, s81, 0x100
	s_addc_u32 vcc_lo, vcc_lo, 0
	s_cmp_gt_u32 vcc_hi, 13
	s_cbranch_scc0 .LBB0_322
	s_and_b64 vcc, exec, s[58:59]
	s_cbranch_vccz .LBB0_325
	s_barrier

; #define PG8_STAGE(bufoff, gbase, voff) do { _Pragma("unroll") for (int _i = 0; _i < 2; ++_i) \
;         __builtin_amdgcn_global_load_lds((const unsigned*)((const char*)(gbase) + (voff)[_i]), (LAS unsigned*)(lds + (bufoff) + ldsw + _i * 8192), 16, 0, 0); } while (0)
; #define PG8_LDA(dst, b, h) do { _Pragma("unroll") for (int m = 0; m < 4; ++m) _Pragma("unroll") for (int k = 0; k < 2; ++k) dst[m][k] = *(const LAS bf16x8*)(lds + PG8_SA(b, h) + aoff + m * 2048 + k * 1024); } while (0)
; #define PG8_LDB(dst, b, h) do { _Pragma("unroll") for (int n = 0; n < 2; ++n) _Pragma("unroll") for (int k = 0; k < 2; ++k) dst[n][k] = *(const LAS bf16x8*)(lds + PG8_SB(b, h) + boff + n * 2048 + k * 1024); } while (0)
; #define PG8_MMA(ai, bj, At, Bt) do { __builtin_amdgcn_s_setprio(1); _Pragma("unroll") for (int m = 0; m < 4; ++m) _Pragma("unroll") for (int n = 0; n < 2; ++n) _Pragma("unroll") for (int k = 0; k < 2; ++k) \
;         acc[ai][bj][m][n] = __builtin_amdgcn_mfma_f32_16x16x32_bf16(Bt[n][k], At[m][k], acc[ai][bj][m][n], 0, 0, 0); __builtin_amdgcn_s_setprio(0); } while (0)
; #define PG8_WAIT_V(n) asm volatile("s_waitcnt vmcnt(" #n ")" ::: "memory")
; #define PG8_WAIT_L(n) asm volatile("s_waitcnt lgkmcnt(" #n ")" ::: "memory")
; #define PG8_BAR __builtin_amdgcn_s_barrier()
; template <class Epi>
; __device__ __forceinline__ void gemm_phase(LAS unsigned char* lds, const Gemm g, const StaticOrder& S, const Epi& E) {
;     ...
;         for (int t = 0; t < nt; t += 2) {
;             const bool last = (t == nt - 2);
;             const char* a1 = cA + (size_t)(t + 1) * kstep;
;             const char* a2 = last ? nA : cA + (size_t)(t + 2) * kstep; const char* b2 = last ? nB : cB + (size_t)(t + 2) * kstep;
;             const char* a3 = a2 + kstep; const char* b3 = b2 + kstep;
;             if constexpr (Epi::MIDK > 0) { if (t == Epi::MIDK) E.mid(acc, cur, wr, wc, fr, fq); }
;             PG8_LDB(B0, 0, 0); PG8_LDB(B1, 0, 1); PG8_SCHED; PG8_LDA(At, 0, 0); PG8_STAGE(PG8_SA(1, 1), a1 + hstep, voffA);
;             PG8_WAIT_V(8); PG8_WAIT_L(0); PG8_BAR; PG8_MMA(0, 0, At, B0); PG8_MMA(0, 1, At, B1); PG8_BAR; PG8_SCHED;
;             PG8_LDA(At, 0, 1); PG8_STAGE(PG8_SB(0, 0), b2, voffB); PG8_STAGE(PG8_SB(0, 1), b2 + hstep, voffB); PG8_STAGE(PG8_SA(0, 0), a2, voffA);
;             PG8_WAIT_V(8); PG8_WAIT_L(0); PG8_BAR; PG8_MMA(1, 0, At, B0); PG8_MMA(1, 1, At, B1); PG8_BAR; PG8_SCHED;
.LBB0_619:
	ds_read_b128 v[154:157], v174
	ds_read_b128 v[158:161], v174 offset:1024
	ds_read_b128 v[162:165], v174 offset:2048
	ds_read_b128 v[166:169], v174 offset:3072
	ds_read_b128 v[182:185], v175
	ds_read_b128 v[186:189], v175 offset:1024
	ds_read_b128 v[190:193], v175 offset:2048
	ds_read_b128 v[194:197], v175 offset:3072
	s_add_u32 s46, s44, 0xfffc0080
	s_addc_u32 s47, s45, -1
	s_cmp_eq_u32 s69, 12
	s_cselect_b32 s49, s64, s47
	s_cselect_b32 s48, s65, s46
	s_cselect_b32 s47, s25, s68
	s_cselect_b32 s46, s66, s67
	s_add_i32 m0, s43, 0xc000
	ds_read_b128 v[204:207], v176
	ds_read_b128 v[208:211], v176 offset:1024
	ds_read_b128 v[212:215], v176 offset:2048
	ds_read_b128 v[216:219], v176 offset:3072
	ds_read_b128 v[220:223], v176 offset:4096
	ds_read_b128 v[224:227], v176 offset:5120
	ds_read_b128 v[228:231], v176 offset:6144
	ds_read_b128 v[232:235], v176 offset:7168
	global_load_lds_dwordx4 v144, s[44:45]
	s_add_i32 m0, s43, 0xe000
	s_nop 0
	global_load_lds_dwordx4 v146, s[44:45]
	s_waitcnt vmcnt(8)
	s_waitcnt lgkmcnt(0)
	s_setprio 1
	s_barrier
	v_mfma_f32_16x16x32_bf16 v[126:129], v[154:157], v[204:207], v[126:129]
	v_mfma_f32_16x16x32_bf16 v[122:125], v[162:165], v[204:207], v[122:125]
	v_mfma_f32_16x16x32_bf16 v[110:113], v[154:157], v[212:215], v[110:113]
	v_mfma_f32_16x16x32_bf16 v[106:109], v[162:165], v[212:215], v[106:109]
	v_mfma_f32_16x16x32_bf16 v[94:97], v[154:157], v[220:223], v[94:97]
	v_mfma_f32_16x16x32_bf16 v[90:93], v[162:165], v[220:223], v[90:93]
	v_mfma_f32_16x16x32_bf16 v[78:81], v[154:157], v[228:231], v[78:81]
	v_mfma_f32_16x16x32_bf16 v[74:77], v[162:165], v[228:231], v[74:77]
	v_mfma_f32_16x16x32_bf16 v[126:129], v[158:161], v[208:211], v[126:129]
	v_mfma_f32_16x16x32_bf16 v[122:125], v[166:169], v[208:211], v[122:125]
	v_mfma_f32_16x16x32_bf16 v[110:113], v[158:161], v[216:219], v[110:113]
	v_mfma_f32_16x16x32_bf16 v[106:109], v[166:169], v[216:219], v[106:109]
	v_mfma_f32_16x16x32_bf16 v[94:97], v[158:161], v[224:227], v[94:97]
	v_mfma_f32_16x16x32_bf16 v[90:93], v[166:169], v[224:227], v[90:93]
	v_mfma_f32_16x16x32_bf16 v[78:81], v[158:161], v[232:235], v[78:81]
	v_mfma_f32_16x16x32_bf16 v[74:77], v[166:169], v[232:235], v[74:77]
	v_mfma_f32_16x16x32_bf16 v[118:121], v[182:185], v[204:207], v[118:121]
	v_mfma_f32_16x16x32_bf16 v[114:117], v[190:193], v[204:207], v[114:117]
	v_mfma_f32_16x16x32_bf16 v[102:105], v[182:185], v[212:215], v[102:105]
	v_mfma_f32_16x16x32_bf16 v[98:101], v[190:193], v[212:215], v[98:101]
	v_mfma_f32_16x16x32_bf16 v[86:89], v[182:185], v[220:223], v[86:89]
	v_mfma_f32_16x16x32_bf16 v[82:85], v[190:193], v[220:223], v[82:85]
	v_mfma_f32_16x16x32_bf16 v[70:73], v[182:185], v[228:231], v[70:73]
	v_mfma_f32_16x16x32_bf16 v[66:69], v[190:193], v[228:231], v[66:69]
	v_mfma_f32_16x16x32_bf16 v[118:121], v[186:189], v[208:211], v[118:121]
	v_mfma_f32_16x16x32_bf16 v[114:117], v[194:197], v[208:211], v[114:117]
	v_mfma_f32_16x16x32_bf16 v[102:105], v[186:189], v[216:219], v[102:105]
	v_mfma_f32_16x16x32_bf16 v[98:101], v[194:197], v[216:219], v[98:101]
	v_mfma_f32_16x16x32_bf16 v[86:89], v[186:189], v[224:227], v[86:89]
	v_mfma_f32_16x16x32_bf16 v[82:85], v[194:197], v[224:227], v[82:85]
	v_mfma_f32_16x16x32_bf16 v[70:73], v[186:189], v[232:235], v[70:73]
	v_mfma_f32_16x16x32_bf16 v[66:69], v[194:197], v[232:235], v[66:69]
	s_barrier
	s_setprio 0
	s_add_u32 s98, s46, s8
	s_addc_u32 s99, s47, s9
	s_add_u32 s100, s48, s8
	s_addc_u32 s101, s49, s9
	s_add_i32 s76, s60, s6
	s_mov_b32 m0, s76
	ds_read_b128 v[204:207], v176 offset:16384
	ds_read_b128 v[208:211], v176 offset:17408
	ds_read_b128 v[212:215], v176 offset:18432
	ds_read_b128 v[216:219], v176 offset:19456
	ds_read_b128 v[220:223], v176 offset:20480
	ds_read_b128 v[224:227], v176 offset:21504
	ds_read_b128 v[228:231], v176 offset:22528
	ds_read_b128 v[232:235], v176 offset:23552
	global_load_lds_dwordx4 v132, s[46:47]
	s_add_i32 m0, s76, 0x2000
	s_add_u32 s76, s46, 0x40000
	s_addc_u32 s77, s47, 0
	s_add_i32 s78, s61, s6
	global_load_lds_dwordx4 v136, s[46:47]
	s_mov_b32 m0, s78
	s_nop 0
	global_load_lds_dwordx4 v132, s[76:77]
	s_add_i32 m0, s78, 0x2000
	s_nop 0
	global_load_lds_dwordx4 v136, s[76:77]
	s_mov_b32 m0, s43
	s_nop 0
	global_load_lds_dwordx4 v130, s[48:49]
	s_mov_b32 m0, s51
	s_nop 0
	global_load_lds_dwordx4 v134, s[48:49]
	s_waitcnt vmcnt(8)
	s_waitcnt lgkmcnt(0)
	s_setprio 1
	s_barrier
	v_mfma_f32_16x16x32_bf16 v[62:65], v[154:157], v[204:207], v[62:65]
	v_mfma_f32_16x16x32_bf16 v[58:61], v[162:165], v[204:207], v[58:61]
	v_mfma_f32_16x16x32_bf16 v[46:49], v[154:157], v[212:215], v[46:49]
	v_mfma_f32_16x16x32_bf16 v[42:45], v[162:165], v[212:215], v[42:45]
	v_mfma_f32_16x16x32_bf16 v[30:33], v[154:157], v[220:223], v[30:33]
	v_mfma_f32_16x16x32_bf16 v[26:29], v[162:165], v[220:223], v[26:29]
	v_mfma_f32_16x16x32_bf16 v[14:17], v[154:157], v[228:231], v[14:17]
	v_mfma_f32_16x16x32_bf16 v[10:13], v[162:165], v[228:231], v[10:13]
	v_mfma_f32_16x16x32_bf16 v[62:65], v[158:161], v[208:211], v[62:65]
	v_mfma_f32_16x16x32_bf16 v[58:61], v[166:169], v[208:211], v[58:61]
	v_mfma_f32_16x16x32_bf16 v[46:49], v[158:161], v[216:219], v[46:49]
	v_mfma_f32_16x16x32_bf16 v[42:45], v[166:169], v[216:219], v[42:45]
	v_mfma_f32_16x16x32_bf16 v[30:33], v[158:161], v[224:227], v[30:33]
	v_mfma_f32_16x16x32_bf16 v[26:29], v[166:169], v[224:227], v[26:29]
	v_mfma_f32_16x16x32_bf16 v[14:17], v[158:161], v[232:235], v[14:17]
	v_mfma_f32_16x16x32_bf16 v[10:13], v[166:169], v[232:235], v[10:13]
	v_mfma_f32_16x16x32_bf16 v[54:57], v[182:185], v[204:207], v[54:57]
	v_mfma_f32_16x16x32_bf16 v[50:53], v[190:193], v[204:207], v[50:53]
	v_mfma_f32_16x16x32_bf16 v[38:41], v[182:185], v[212:215], v[38:41]
	v_mfma_f32_16x16x32_bf16 v[34:37], v[190:193], v[212:215], v[34:37]
	v_mfma_f32_16x16x32_bf16 v[22:25], v[182:185], v[220:223], v[22:25]
	v_mfma_f32_16x16x32_bf16 v[18:21], v[190:193], v[220:223], v[18:21]
	v_mfma_f32_16x16x32_bf16 v[6:9], v[182:185], v[228:231], v[6:9]
	v_mfma_f32_16x16x32_bf16 v[2:5], v[190:193], v[228:231], v[2:5]
	v_mfma_f32_16x16x32_bf16 v[54:57], v[186:189], v[208:211], v[54:57]
	v_mfma_f32_16x16x32_bf16 v[50:53], v[194:197], v[208:211], v[50:53]
	v_mfma_f32_16x16x32_bf16 v[38:41], v[186:189], v[216:219], v[38:41]
	v_mfma_f32_16x16x32_bf16 v[34:37], v[194:197], v[216:219], v[34:37]
	v_mfma_f32_16x16x32_bf16 v[22:25], v[186:189], v[224:227], v[22:25]
	v_mfma_f32_16x16x32_bf16 v[18:21], v[194:197], v[224:227], v[18:21]
	v_mfma_f32_16x16x32_bf16 v[6:9], v[186:189], v[232:235], v[6:9]
	v_mfma_f32_16x16x32_bf16 v[2:5], v[194:197], v[232:235], v[2:5]
	s_barrier
; #define PG8_STAGE(bufoff, gbase, voff) do { _Pragma("unroll") for (int _i = 0; _i < 2; ++_i) \
;         __builtin_amdgcn_global_load_lds((const unsigned*)((const char*)(gbase) + (voff)[_i]), (LAS unsigned*)(lds + (bufoff) + ldsw + _i * 8192), 16, 0, 0); } while (0)
; #define PG8_LDA(dst, b, h) do { _Pragma("unroll") for (int m = 0; m < 4; ++m) _Pragma("unroll") for (int k = 0; k < 2; ++k) dst[m][k] = *(const LAS bf16x8*)(lds + PG8_SA(b, h) + aoff + m * 2048 + k * 1024); } while (0)
; #define PG8_LDB(dst, b, h) do { _Pragma("unroll") for (int n = 0; n < 2; ++n) _Pragma("unroll") for (int k = 0; k < 2; ++k) dst[n][k] = *(const LAS bf16x8*)(lds + PG8_SB(b, h) + boff + n * 2048 + k * 1024); } while (0)
; #define PG8_MMA(ai, bj, At, Bt) do { __builtin_amdgcn_s_setprio(1); _Pragma("unroll") for (int m = 0; m < 4; ++m) _Pragma("unroll") for (int n = 0; n < 2; ++n) _Pragma("unroll") for (int k = 0; k < 2; ++k) \
;         acc[ai][bj][m][n] = __builtin_amdgcn_mfma_f32_16x16x32_bf16(Bt[n][k], At[m][k], acc[ai][bj][m][n], 0, 0, 0); __builtin_amdgcn_s_setprio(0); } while (0)
; #define PG8_WAIT_V(n) asm volatile("s_waitcnt vmcnt(" #n ")" ::: "memory")
; #define PG8_WAIT_L(n) asm volatile("s_waitcnt lgkmcnt(" #n ")" ::: "memory")
; #define PG8_BAR __builtin_amdgcn_s_barrier()
; #define PG8_SCHED __builtin_amdgcn_sched_barrier(0)
; template <class Epi>
; __device__ __forceinline__ void gemm_phase(LAS unsigned char* lds, const Gemm g, const StaticOrder& S, const Epi& E) {
;     ...
;         for (int t = 0; t < nt; t += 2) {
;     ...
;             PG8_LDB(B0, 1, 0); PG8_LDB(B1, 1, 1); PG8_SCHED; PG8_LDA(At, 1, 0); PG8_STAGE(PG8_SA(0, 1), a2 + hstep, voffA);
;             PG8_WAIT_V(8); PG8_WAIT_L(0); PG8_BAR; PG8_MMA(0, 0, At, B0); PG8_MMA(0, 1, At, B1); PG8_BAR; PG8_SCHED;
;             PG8_LDA(At, 1, 1); PG8_STAGE(PG8_SB(1, 0), b3, voffB); PG8_STAGE(PG8_SB(1, 1), b3 + hstep, voffB); PG8_STAGE(PG8_SA(1, 0), a3, voffA);
;             PG8_WAIT_V(8); PG8_WAIT_L(0); PG8_BAR; PG8_MMA(1, 0, At, B0); PG8_MMA(1, 1, At, B1); PG8_BAR; PG8_SCHED;
;         }
;         if (wr == 0) PG8_BAR;
	s_setprio 0
	s_add_i32 s76, 0, 0x18000
	v_add_u32_e32 v138, s76, v172
	s_add_i32 s77, 0, 0x1c000
	ds_read_b128 v[154:157], v138
	ds_read_b128 v[158:161], v138 offset:1024
	ds_read_b128 v[162:165], v138 offset:2048
	ds_read_b128 v[166:169], v138 offset:3072
	v_add_u32_e32 v138, s77, v172
	ds_read_b128 v[182:185], v138
	ds_read_b128 v[186:189], v138 offset:1024
	ds_read_b128 v[190:193], v138 offset:2048
	ds_read_b128 v[194:197], v138 offset:3072
	s_add_u32 s48, s48, 0x40000
	s_addc_u32 s49, s49, 0
	s_mov_b32 m0, s52
	ds_read_b128 v[204:207], v176 offset:32768
	ds_read_b128 v[208:211], v176 offset:33792
	ds_read_b128 v[212:215], v176 offset:34816
	ds_read_b128 v[216:219], v176 offset:35840
	ds_read_b128 v[220:223], v176 offset:36864
	ds_read_b128 v[224:227], v176 offset:37888
	ds_read_b128 v[228:231], v176 offset:38912
	ds_read_b128 v[232:235], v176 offset:39936
	global_load_lds_dwordx4 v130, s[48:49]
	s_mov_b32 m0, s53
	s_nop 0
	global_load_lds_dwordx4 v134, s[48:49]
	s_waitcnt vmcnt(8)
	s_waitcnt lgkmcnt(0)
	s_setprio 1
	s_barrier
	v_mfma_f32_16x16x32_bf16 v[126:129], v[154:157], v[204:207], v[126:129]
	v_mfma_f32_16x16x32_bf16 v[122:125], v[162:165], v[204:207], v[122:125]
	v_mfma_f32_16x16x32_bf16 v[110:113], v[154:157], v[212:215], v[110:113]
	v_mfma_f32_16x16x32_bf16 v[106:109], v[162:165], v[212:215], v[106:109]
	v_mfma_f32_16x16x32_bf16 v[94:97], v[154:157], v[220:223], v[94:97]
	v_mfma_f32_16x16x32_bf16 v[90:93], v[162:165], v[220:223], v[90:93]
	v_mfma_f32_16x16x32_bf16 v[78:81], v[154:157], v[228:231], v[78:81]
	v_mfma_f32_16x16x32_bf16 v[74:77], v[162:165], v[228:231], v[74:77]
	v_mfma_f32_16x16x32_bf16 v[126:129], v[158:161], v[208:211], v[126:129]
	v_mfma_f32_16x16x32_bf16 v[122:125], v[166:169], v[208:211], v[122:125]
	v_mfma_f32_16x16x32_bf16 v[110:113], v[158:161], v[216:219], v[110:113]
	v_mfma_f32_16x16x32_bf16 v[106:109], v[166:169], v[216:219], v[106:109]
	v_mfma_f32_16x16x32_bf16 v[94:97], v[158:161], v[224:227], v[94:97]
	v_mfma_f32_16x16x32_bf16 v[90:93], v[166:169], v[224:227], v[90:93]
	v_mfma_f32_16x16x32_bf16 v[78:81], v[158:161], v[232:235], v[78:81]
	v_mfma_f32_16x16x32_bf16 v[74:77], v[166:169], v[232:235], v[74:77]
	v_mfma_f32_16x16x32_bf16 v[118:121], v[182:185], v[204:207], v[118:121]
	v_mfma_f32_16x16x32_bf16 v[114:117], v[190:193], v[204:207], v[114:117]
	v_mfma_f32_16x16x32_bf16 v[102:105], v[182:185], v[212:215], v[102:105]
	v_mfma_f32_16x16x32_bf16 v[98:101], v[190:193], v[212:215], v[98:101]
	v_mfma_f32_16x16x32_bf16 v[86:89], v[182:185], v[220:223], v[86:89]
	v_mfma_f32_16x16x32_bf16 v[82:85], v[190:193], v[220:223], v[82:85]
	v_mfma_f32_16x16x32_bf16 v[70:73], v[182:185], v[228:231], v[70:73]
	v_mfma_f32_16x16x32_bf16 v[66:69], v[190:193], v[228:231], v[66:69]
	v_mfma_f32_16x16x32_bf16 v[118:121], v[186:189], v[208:211], v[118:121]
	v_mfma_f32_16x16x32_bf16 v[114:117], v[194:197], v[208:211], v[114:117]
	v_mfma_f32_16x16x32_bf16 v[102:105], v[186:189], v[216:219], v[102:105]
	v_mfma_f32_16x16x32_bf16 v[98:101], v[194:197], v[216:219], v[98:101]
	v_mfma_f32_16x16x32_bf16 v[86:89], v[186:189], v[224:227], v[86:89]
	v_mfma_f32_16x16x32_bf16 v[82:85], v[194:197], v[224:227], v[82:85]
	v_mfma_f32_16x16x32_bf16 v[70:73], v[186:189], v[232:235], v[70:73]
	v_mfma_f32_16x16x32_bf16 v[66:69], v[194:197], v[232:235], v[66:69]
	s_barrier
	s_setprio 0
	s_add_i32 s48, s76, s6
	s_mov_b32 m0, s48
	ds_read_b128 v[204:207], v176 offset:49152
	ds_read_b128 v[208:211], v176 offset:50176
	ds_read_b128 v[212:215], v176 offset:51200
	ds_read_b128 v[216:219], v176 offset:52224
	ds_read_b128 v[220:223], v176 offset:53248
	ds_read_b128 v[224:227], v176 offset:54272
	ds_read_b128 v[228:231], v176 offset:55296
	ds_read_b128 v[232:235], v176 offset:56320
	global_load_lds_dwordx4 v132, s[98:99]
	s_add_i32 m0, s48, 0x2000
	s_add_u32 s46, s46, 0x40080
	s_addc_u32 s47, s47, 0
	s_add_i32 s48, s77, s6
	global_load_lds_dwordx4 v136, s[98:99]
	s_mov_b32 m0, s48
	s_nop 0
	global_load_lds_dwordx4 v132, s[46:47]
	s_add_i32 m0, s48, 0x2000
	s_nop 0
	global_load_lds_dwordx4 v136, s[46:47]
	s_mov_b32 m0, s56
	s_nop 0
	global_load_lds_dwordx4 v130, s[100:101]
	s_mov_b32 m0, s57
	s_nop 0
	global_load_lds_dwordx4 v134, s[100:101]
	s_waitcnt vmcnt(8)
	s_waitcnt lgkmcnt(0)
	s_setprio 1
	s_barrier
	v_mfma_f32_16x16x32_bf16 v[62:65], v[154:157], v[204:207], v[62:65]
	v_mfma_f32_16x16x32_bf16 v[58:61], v[162:165], v[204:207], v[58:61]
	v_mfma_f32_16x16x32_bf16 v[46:49], v[154:157], v[212:215], v[46:49]
	v_mfma_f32_16x16x32_bf16 v[42:45], v[162:165], v[212:215], v[42:45]
	v_mfma_f32_16x16x32_bf16 v[30:33], v[154:157], v[220:223], v[30:33]
	v_mfma_f32_16x16x32_bf16 v[26:29], v[162:165], v[220:223], v[26:29]
	v_mfma_f32_16x16x32_bf16 v[14:17], v[154:157], v[228:231], v[14:17]
	v_mfma_f32_16x16x32_bf16 v[10:13], v[162:165], v[228:231], v[10:13]
	v_mfma_f32_16x16x32_bf16 v[62:65], v[158:161], v[208:211], v[62:65]
	v_mfma_f32_16x16x32_bf16 v[58:61], v[166:169], v[208:211], v[58:61]
	v_mfma_f32_16x16x32_bf16 v[46:49], v[158:161], v[216:219], v[46:49]
	v_mfma_f32_16x16x32_bf16 v[42:45], v[166:169], v[216:219], v[42:45]
	v_mfma_f32_16x16x32_bf16 v[30:33], v[158:161], v[224:227], v[30:33]
	v_mfma_f32_16x16x32_bf16 v[26:29], v[166:169], v[224:227], v[26:29]
	v_mfma_f32_16x16x32_bf16 v[14:17], v[158:161], v[232:235], v[14:17]
	v_mfma_f32_16x16x32_bf16 v[10:13], v[166:169], v[232:235], v[10:13]
	v_mfma_f32_16x16x32_bf16 v[54:57], v[182:185], v[204:207], v[54:57]
	v_mfma_f32_16x16x32_bf16 v[50:53], v[190:193], v[204:207], v[50:53]
	v_mfma_f32_16x16x32_bf16 v[38:41], v[182:185], v[212:215], v[38:41]
	v_mfma_f32_16x16x32_bf16 v[34:37], v[190:193], v[212:215], v[34:37]
	v_mfma_f32_16x16x32_bf16 v[22:25], v[182:185], v[220:223], v[22:25]
	v_mfma_f32_16x16x32_bf16 v[18:21], v[190:193], v[220:223], v[18:21]
	v_mfma_f32_16x16x32_bf16 v[6:9], v[182:185], v[228:231], v[6:9]
	v_mfma_f32_16x16x32_bf16 v[2:5], v[190:193], v[228:231], v[2:5]
	v_mfma_f32_16x16x32_bf16 v[54:57], v[186:189], v[208:211], v[54:57]
	v_mfma_f32_16x16x32_bf16 v[50:53], v[194:197], v[208:211], v[50:53]
	v_mfma_f32_16x16x32_bf16 v[38:41], v[186:189], v[216:219], v[38:41]
	v_mfma_f32_16x16x32_bf16 v[34:37], v[194:197], v[216:219], v[34:37]
	v_mfma_f32_16x16x32_bf16 v[22:25], v[186:189], v[224:227], v[22:25]
	v_mfma_f32_16x16x32_bf16 v[18:21], v[194:197], v[224:227], v[18:21]
	v_mfma_f32_16x16x32_bf16 v[6:9], v[186:189], v[232:235], v[6:9]
	v_mfma_f32_16x16x32_bf16 v[2:5], v[194:197], v[232:235], v[2:5]
	s_barrier
	s_setprio 0
	s_add_i32 s69, s69, 2
	s_add_u32 s44, s44, 0x100
	s_addc_u32 s45, s45, 0
	s_add_u32 s67, s67, 0x100
	s_addc_u32 s68, s68, 0
	s_cmp_gt_u32 s69, 13
	s_cbranch_scc0 .LBB0_619
	s_and_b64 vcc, exec, s[18:19]
	s_cbranch_vccz .LBB0_622
	s_barrier

; #define PG8_STAGE(bufoff, gbase, voff) do { _Pragma("unroll") for (int _i = 0; _i < 2; ++_i) \
;         __builtin_amdgcn_global_load_lds((const unsigned*)((const char*)(gbase) + (voff)[_i]), (LAS unsigned*)(lds + (bufoff) + ldsw + _i * 8192), 16, 0, 0); } while (0)
; #define PG8_LDA(dst, b, h) do { _Pragma("unroll") for (int m = 0; m < 4; ++m) _Pragma("unroll") for (int k = 0; k < 2; ++k) dst[m][k] = *(const LAS bf16x8*)(lds + PG8_SA(b, h) + aoff + m * 2048 + k * 1024); } while (0)
; #define PG8_LDB(dst, b, h) do { _Pragma("unroll") for (int n = 0; n < 2; ++n) _Pragma("unroll") for (int k = 0; k < 2; ++k) dst[n][k] = *(const LAS bf16x8*)(lds + PG8_SB(b, h) + boff + n * 2048 + k * 1024); } while (0)
; #define PG8_MMA(ai, bj, At, Bt) do { __builtin_amdgcn_s_setprio(1); _Pragma("unroll") for (int m = 0; m < 4; ++m) _Pragma("unroll") for (int n = 0; n < 2; ++n) _Pragma("unroll") for (int k = 0; k < 2; ++k) \
;         acc[ai][bj][m][n] = __builtin_amdgcn_mfma_f32_16x16x32_bf16(Bt[n][k], At[m][k], acc[ai][bj][m][n], 0, 0, 0); __builtin_amdgcn_s_setprio(0); } while (0)
; #define PG8_WAIT_V(n) asm volatile("s_waitcnt vmcnt(" #n ")" ::: "memory")
; #define PG8_WAIT_L(n) asm volatile("s_waitcnt lgkmcnt(" #n ")" ::: "memory")
; #define PG8_BAR __builtin_amdgcn_s_barrier()
; template <class Epi>
; __device__ __forceinline__ void gemm_phase(LAS unsigned char* lds, const Gemm g, const StaticOrder& S, const Epi& E) {
;     ...
;         for (int t = 0; t < nt; t += 2) {
;             const bool last = (t == nt - 2);
;             const char* a1 = cA + (size_t)(t + 1) * kstep;
;             const char* a2 = last ? nA : cA + (size_t)(t + 2) * kstep; const char* b2 = last ? nB : cB + (size_t)(t + 2) * kstep;
;             const char* a3 = a2 + kstep; const char* b3 = b2 + kstep;
;             if constexpr (Epi::MIDK > 0) { if (t == Epi::MIDK) E.mid(acc, cur, wr, wc, fr, fq); }
;             PG8_LDB(B0, 0, 0); PG8_LDB(B1, 0, 1); PG8_SCHED; PG8_LDA(At, 0, 0); PG8_STAGE(PG8_SA(1, 1), a1 + hstep, voffA);
;             PG8_WAIT_V(8); PG8_WAIT_L(0); PG8_BAR; PG8_MMA(0, 0, At, B0); PG8_MMA(0, 1, At, B1); PG8_BAR; PG8_SCHED;
;             PG8_LDA(At, 0, 1); PG8_STAGE(PG8_SB(0, 0), b2, voffB); PG8_STAGE(PG8_SB(0, 1), b2 + hstep, voffB); PG8_STAGE(PG8_SA(0, 0), a2, voffA);
;             PG8_WAIT_V(8); PG8_WAIT_L(0); PG8_BAR; PG8_MMA(1, 0, At, B0); PG8_MMA(1, 1, At, B1); PG8_BAR; PG8_SCHED;
.LBB0_785:
	ds_read_b128 v[130:133], v162
	ds_read_b128 v[134:137], v162 offset:1024
	ds_read_b128 v[154:157], v162 offset:2048
	ds_read_b128 v[166:169], v162 offset:3072
	ds_read_b128 v[174:177], v163
	ds_read_b128 v[178:181], v163 offset:1024
	ds_read_b128 v[182:185], v163 offset:2048
	ds_read_b128 v[186:189], v163 offset:3072
	s_add_u32 s40, s38, 0xfffc0080
	s_addc_u32 s41, s39, -1
	s_cmp_eq_u32 s63, 12
	s_cselect_b32 s43, s21, s41
	s_cselect_b32 s42, s27, s40
	s_cselect_b32 s41, s19, s62
	s_cselect_b32 s40, s60, s61
	s_add_i32 m0, s45, 0xc000
	ds_read_b128 v[196:199], v164
	ds_read_b128 v[200:203], v164 offset:1024
	ds_read_b128 v[204:207], v164 offset:2048
	ds_read_b128 v[208:211], v164 offset:3072
	ds_read_b128 v[212:215], v164 offset:4096
	ds_read_b128 v[216:219], v164 offset:5120
	ds_read_b128 v[220:223], v164 offset:6144
	ds_read_b128 v[224:227], v164 offset:7168
	global_load_lds_dwordx4 v146, s[38:39]
	s_add_i32 m0, s45, 0xe000
	s_nop 0
	global_load_lds_dwordx4 v148, s[38:39]
	s_waitcnt vmcnt(8)
	s_waitcnt lgkmcnt(0)
	s_setprio 1
	s_barrier
	v_mfma_f32_16x16x32_bf16 v[126:129], v[130:133], v[196:199], v[126:129]
	v_mfma_f32_16x16x32_bf16 v[122:125], v[154:157], v[196:199], v[122:125]
	v_mfma_f32_16x16x32_bf16 v[110:113], v[130:133], v[204:207], v[110:113]
	v_mfma_f32_16x16x32_bf16 v[106:109], v[154:157], v[204:207], v[106:109]
	v_mfma_f32_16x16x32_bf16 v[94:97], v[130:133], v[212:215], v[94:97]
	v_mfma_f32_16x16x32_bf16 v[90:93], v[154:157], v[212:215], v[90:93]
	v_mfma_f32_16x16x32_bf16 v[78:81], v[130:133], v[220:223], v[78:81]
	v_mfma_f32_16x16x32_bf16 v[74:77], v[154:157], v[220:223], v[74:77]
	v_mfma_f32_16x16x32_bf16 v[126:129], v[134:137], v[200:203], v[126:129]
	v_mfma_f32_16x16x32_bf16 v[122:125], v[166:169], v[200:203], v[122:125]
	v_mfma_f32_16x16x32_bf16 v[110:113], v[134:137], v[208:211], v[110:113]
	v_mfma_f32_16x16x32_bf16 v[106:109], v[166:169], v[208:211], v[106:109]
	v_mfma_f32_16x16x32_bf16 v[94:97], v[134:137], v[216:219], v[94:97]
	v_mfma_f32_16x16x32_bf16 v[90:93], v[166:169], v[216:219], v[90:93]
	v_mfma_f32_16x16x32_bf16 v[78:81], v[134:137], v[224:227], v[78:81]
	v_mfma_f32_16x16x32_bf16 v[74:77], v[166:169], v[224:227], v[74:77]
	v_mfma_f32_16x16x32_bf16 v[118:121], v[174:177], v[196:199], v[118:121]
	v_mfma_f32_16x16x32_bf16 v[114:117], v[182:185], v[196:199], v[114:117]
	v_mfma_f32_16x16x32_bf16 v[102:105], v[174:177], v[204:207], v[102:105]
	v_mfma_f32_16x16x32_bf16 v[98:101], v[182:185], v[204:207], v[98:101]
	v_mfma_f32_16x16x32_bf16 v[86:89], v[174:177], v[212:215], v[86:89]
	v_mfma_f32_16x16x32_bf16 v[82:85], v[182:185], v[212:215], v[82:85]
	v_mfma_f32_16x16x32_bf16 v[70:73], v[174:177], v[220:223], v[70:73]
	v_mfma_f32_16x16x32_bf16 v[66:69], v[182:185], v[220:223], v[66:69]
	v_mfma_f32_16x16x32_bf16 v[118:121], v[178:181], v[200:203], v[118:121]
	v_mfma_f32_16x16x32_bf16 v[114:117], v[186:189], v[200:203], v[114:117]
	v_mfma_f32_16x16x32_bf16 v[102:105], v[178:181], v[208:211], v[102:105]
	v_mfma_f32_16x16x32_bf16 v[98:101], v[186:189], v[208:211], v[98:101]
	v_mfma_f32_16x16x32_bf16 v[86:89], v[178:181], v[216:219], v[86:89]
	v_mfma_f32_16x16x32_bf16 v[82:85], v[186:189], v[216:219], v[82:85]
	v_mfma_f32_16x16x32_bf16 v[70:73], v[178:181], v[224:227], v[70:73]
	v_mfma_f32_16x16x32_bf16 v[66:69], v[186:189], v[224:227], v[66:69]
	s_barrier
	s_setprio 0
	s_add_u32 s98, s40, s12
	s_addc_u32 s99, s41, s13
	s_add_u32 s100, s42, s12
	s_addc_u32 s101, s43, s13
	s_add_i32 s64, s57, s44
	s_mov_b32 m0, s64
	ds_read_b128 v[196:199], v164 offset:16384
	ds_read_b128 v[200:203], v164 offset:17408
	ds_read_b128 v[204:207], v164 offset:18432
	ds_read_b128 v[208:211], v164 offset:19456
	ds_read_b128 v[212:215], v164 offset:20480
	ds_read_b128 v[216:219], v164 offset:21504
	ds_read_b128 v[220:223], v164 offset:22528
	ds_read_b128 v[224:227], v164 offset:23552
	global_load_lds_dwordx4 v140, s[40:41]
	s_add_i32 m0, s64, 0x2000
	s_add_u32 s64, s40, 0x40000
	s_addc_u32 s65, s41, 0
	s_add_i32 s66, s58, s44
	global_load_lds_dwordx4 v144, s[40:41]
	s_mov_b32 m0, s66
	s_nop 0
	global_load_lds_dwordx4 v140, s[64:65]
	s_add_i32 m0, s66, 0x2000
	s_nop 0
	global_load_lds_dwordx4 v144, s[64:65]
	s_mov_b32 m0, s45
	s_nop 0
	global_load_lds_dwordx4 v138, s[42:43]
	s_mov_b32 m0, s46
	s_nop 0
	global_load_lds_dwordx4 v142, s[42:43]
	s_waitcnt vmcnt(8)
	s_waitcnt lgkmcnt(0)
	s_setprio 1
	s_barrier
	v_mfma_f32_16x16x32_bf16 v[62:65], v[130:133], v[196:199], v[62:65]
	v_mfma_f32_16x16x32_bf16 v[58:61], v[154:157], v[196:199], v[58:61]
	v_mfma_f32_16x16x32_bf16 v[46:49], v[130:133], v[204:207], v[46:49]
	v_mfma_f32_16x16x32_bf16 v[42:45], v[154:157], v[204:207], v[42:45]
	v_mfma_f32_16x16x32_bf16 v[30:33], v[130:133], v[212:215], v[30:33]
	v_mfma_f32_16x16x32_bf16 v[26:29], v[154:157], v[212:215], v[26:29]
	v_mfma_f32_16x16x32_bf16 v[14:17], v[130:133], v[220:223], v[14:17]
	v_mfma_f32_16x16x32_bf16 v[10:13], v[154:157], v[220:223], v[10:13]
	v_mfma_f32_16x16x32_bf16 v[62:65], v[134:137], v[200:203], v[62:65]
	v_mfma_f32_16x16x32_bf16 v[58:61], v[166:169], v[200:203], v[58:61]
	v_mfma_f32_16x16x32_bf16 v[46:49], v[134:137], v[208:211], v[46:49]
	v_mfma_f32_16x16x32_bf16 v[42:45], v[166:169], v[208:211], v[42:45]
	v_mfma_f32_16x16x32_bf16 v[30:33], v[134:137], v[216:219], v[30:33]
	v_mfma_f32_16x16x32_bf16 v[26:29], v[166:169], v[216:219], v[26:29]
	v_mfma_f32_16x16x32_bf16 v[14:17], v[134:137], v[224:227], v[14:17]
	v_mfma_f32_16x16x32_bf16 v[10:13], v[166:169], v[224:227], v[10:13]
	v_mfma_f32_16x16x32_bf16 v[54:57], v[174:177], v[196:199], v[54:57]
	v_mfma_f32_16x16x32_bf16 v[50:53], v[182:185], v[196:199], v[50:53]
	v_mfma_f32_16x16x32_bf16 v[38:41], v[174:177], v[204:207], v[38:41]
	v_mfma_f32_16x16x32_bf16 v[34:37], v[182:185], v[204:207], v[34:37]
	v_mfma_f32_16x16x32_bf16 v[22:25], v[174:177], v[212:215], v[22:25]
	v_mfma_f32_16x16x32_bf16 v[18:21], v[182:185], v[212:215], v[18:21]
	v_mfma_f32_16x16x32_bf16 v[6:9], v[174:177], v[220:223], v[6:9]
	v_mfma_f32_16x16x32_bf16 v[2:5], v[182:185], v[220:223], v[2:5]
	v_mfma_f32_16x16x32_bf16 v[54:57], v[178:181], v[200:203], v[54:57]
	v_mfma_f32_16x16x32_bf16 v[50:53], v[186:189], v[200:203], v[50:53]
	v_mfma_f32_16x16x32_bf16 v[38:41], v[178:181], v[208:211], v[38:41]
	v_mfma_f32_16x16x32_bf16 v[34:37], v[186:189], v[208:211], v[34:37]
	v_mfma_f32_16x16x32_bf16 v[22:25], v[178:181], v[216:219], v[22:25]
	v_mfma_f32_16x16x32_bf16 v[18:21], v[186:189], v[216:219], v[18:21]
	v_mfma_f32_16x16x32_bf16 v[6:9], v[178:181], v[224:227], v[6:9]
	v_mfma_f32_16x16x32_bf16 v[2:5], v[186:189], v[224:227], v[2:5]
	s_barrier
; #define PG8_STAGE(bufoff, gbase, voff) do { _Pragma("unroll") for (int _i = 0; _i < 2; ++_i) \
;         __builtin_amdgcn_global_load_lds((const unsigned*)((const char*)(gbase) + (voff)[_i]), (LAS unsigned*)(lds + (bufoff) + ldsw + _i * 8192), 16, 0, 0); } while (0)
; #define PG8_LDA(dst, b, h) do { _Pragma("unroll") for (int m = 0; m < 4; ++m) _Pragma("unroll") for (int k = 0; k < 2; ++k) dst[m][k] = *(const LAS bf16x8*)(lds + PG8_SA(b, h) + aoff + m * 2048 + k * 1024); } while (0)
; #define PG8_LDB(dst, b, h) do { _Pragma("unroll") for (int n = 0; n < 2; ++n) _Pragma("unroll") for (int k = 0; k < 2; ++k) dst[n][k] = *(const LAS bf16x8*)(lds + PG8_SB(b, h) + boff + n * 2048 + k * 1024); } while (0)
; #define PG8_MMA(ai, bj, At, Bt) do { __builtin_amdgcn_s_setprio(1); _Pragma("unroll") for (int m = 0; m < 4; ++m) _Pragma("unroll") for (int n = 0; n < 2; ++n) _Pragma("unroll") for (int k = 0; k < 2; ++k) \
;         acc[ai][bj][m][n] = __builtin_amdgcn_mfma_f32_16x16x32_bf16(Bt[n][k], At[m][k], acc[ai][bj][m][n], 0, 0, 0); __builtin_amdgcn_s_setprio(0); } while (0)
; #define PG8_WAIT_V(n) asm volatile("s_waitcnt vmcnt(" #n ")" ::: "memory")
; #define PG8_WAIT_L(n) asm volatile("s_waitcnt lgkmcnt(" #n ")" ::: "memory")
; #define PG8_BAR __builtin_amdgcn_s_barrier()
; #define PG8_SCHED __builtin_amdgcn_sched_barrier(0)
; template <class Epi>
; __device__ __forceinline__ void gemm_phase(LAS unsigned char* lds, const Gemm g, const StaticOrder& S, const Epi& E) {
;     ...
;         for (int t = 0; t < nt; t += 2) {
;     ...
;             PG8_LDB(B0, 1, 0); PG8_LDB(B1, 1, 1); PG8_SCHED; PG8_LDA(At, 1, 0); PG8_STAGE(PG8_SA(0, 1), a2 + hstep, voffA);
;             PG8_WAIT_V(8); PG8_WAIT_L(0); PG8_BAR; PG8_MMA(0, 0, At, B0); PG8_MMA(0, 1, At, B1); PG8_BAR; PG8_SCHED;
;             PG8_LDA(At, 1, 1); PG8_STAGE(PG8_SB(1, 0), b3, voffB); PG8_STAGE(PG8_SB(1, 1), b3 + hstep, voffB); PG8_STAGE(PG8_SA(1, 0), a3, voffA);
;             PG8_WAIT_V(8); PG8_WAIT_L(0); PG8_BAR; PG8_MMA(1, 0, At, B0); PG8_MMA(1, 1, At, B1); PG8_BAR; PG8_SCHED;
;         }
;         if (wr == 0) PG8_BAR;
	s_setprio 0
	s_add_i32 s64, 0, 0x18000
	s_add_i32 s65, 0, 0x1c000
	v_add_u32_e32 v166, s64, v160
	v_add_u32_e32 v186, s65, v160
	ds_read_b128 v[130:133], v166
	ds_read_b128 v[134:137], v166 offset:1024
	ds_read_b128 v[154:157], v166 offset:2048
	ds_read_b128 v[166:169], v166 offset:3072
	ds_read_b128 v[174:177], v186
	ds_read_b128 v[178:181], v186 offset:1024
	ds_read_b128 v[182:185], v186 offset:2048
	ds_read_b128 v[186:189], v186 offset:3072
	s_add_u32 s42, s42, 0x40000
	s_addc_u32 s43, s43, 0
	s_mov_b32 m0, s47
	ds_read_b128 v[196:199], v164 offset:32768
	ds_read_b128 v[200:203], v164 offset:33792
	ds_read_b128 v[204:207], v164 offset:34816
	ds_read_b128 v[208:211], v164 offset:35840
	ds_read_b128 v[212:215], v164 offset:36864
	ds_read_b128 v[216:219], v164 offset:37888
	ds_read_b128 v[220:223], v164 offset:38912
	ds_read_b128 v[224:227], v164 offset:39936
	global_load_lds_dwordx4 v138, s[42:43]
	s_mov_b32 m0, s48
	s_nop 0
	global_load_lds_dwordx4 v142, s[42:43]
	s_waitcnt vmcnt(8)
	s_waitcnt lgkmcnt(0)
	s_setprio 1
	s_barrier
	v_mfma_f32_16x16x32_bf16 v[126:129], v[130:133], v[196:199], v[126:129]
	v_mfma_f32_16x16x32_bf16 v[122:125], v[154:157], v[196:199], v[122:125]
	v_mfma_f32_16x16x32_bf16 v[110:113], v[130:133], v[204:207], v[110:113]
	v_mfma_f32_16x16x32_bf16 v[106:109], v[154:157], v[204:207], v[106:109]
	v_mfma_f32_16x16x32_bf16 v[94:97], v[130:133], v[212:215], v[94:97]
	v_mfma_f32_16x16x32_bf16 v[90:93], v[154:157], v[212:215], v[90:93]
	v_mfma_f32_16x16x32_bf16 v[78:81], v[130:133], v[220:223], v[78:81]
	v_mfma_f32_16x16x32_bf16 v[74:77], v[154:157], v[220:223], v[74:77]
	v_mfma_f32_16x16x32_bf16 v[126:129], v[134:137], v[200:203], v[126:129]
	v_mfma_f32_16x16x32_bf16 v[122:125], v[166:169], v[200:203], v[122:125]
	v_mfma_f32_16x16x32_bf16 v[110:113], v[134:137], v[208:211], v[110:113]
	v_mfma_f32_16x16x32_bf16 v[106:109], v[166:169], v[208:211], v[106:109]
	v_mfma_f32_16x16x32_bf16 v[94:97], v[134:137], v[216:219], v[94:97]
	v_mfma_f32_16x16x32_bf16 v[90:93], v[166:169], v[216:219], v[90:93]
	v_mfma_f32_16x16x32_bf16 v[78:81], v[134:137], v[224:227], v[78:81]
	v_mfma_f32_16x16x32_bf16 v[74:77], v[166:169], v[224:227], v[74:77]
	v_mfma_f32_16x16x32_bf16 v[118:121], v[174:177], v[196:199], v[118:121]
	v_mfma_f32_16x16x32_bf16 v[114:117], v[182:185], v[196:199], v[114:117]
	v_mfma_f32_16x16x32_bf16 v[102:105], v[174:177], v[204:207], v[102:105]
	v_mfma_f32_16x16x32_bf16 v[98:101], v[182:185], v[204:207], v[98:101]
	v_mfma_f32_16x16x32_bf16 v[86:89], v[174:177], v[212:215], v[86:89]
	v_mfma_f32_16x16x32_bf16 v[82:85], v[182:185], v[212:215], v[82:85]
	v_mfma_f32_16x16x32_bf16 v[70:73], v[174:177], v[220:223], v[70:73]
	v_mfma_f32_16x16x32_bf16 v[66:69], v[182:185], v[220:223], v[66:69]
	v_mfma_f32_16x16x32_bf16 v[118:121], v[178:181], v[200:203], v[118:121]
	v_mfma_f32_16x16x32_bf16 v[114:117], v[186:189], v[200:203], v[114:117]
	v_mfma_f32_16x16x32_bf16 v[102:105], v[178:181], v[208:211], v[102:105]
	v_mfma_f32_16x16x32_bf16 v[98:101], v[186:189], v[208:211], v[98:101]
	v_mfma_f32_16x16x32_bf16 v[86:89], v[178:181], v[216:219], v[86:89]
	v_mfma_f32_16x16x32_bf16 v[82:85], v[186:189], v[216:219], v[82:85]
	v_mfma_f32_16x16x32_bf16 v[70:73], v[178:181], v[224:227], v[70:73]
	v_mfma_f32_16x16x32_bf16 v[66:69], v[186:189], v[224:227], v[66:69]
	s_barrier
	s_setprio 0
	s_add_i32 s42, s64, s44
	s_mov_b32 m0, s42
	ds_read_b128 v[196:199], v164 offset:49152
	ds_read_b128 v[200:203], v164 offset:50176
	ds_read_b128 v[204:207], v164 offset:51200
	ds_read_b128 v[208:211], v164 offset:52224
	ds_read_b128 v[212:215], v164 offset:53248
	ds_read_b128 v[216:219], v164 offset:54272
	ds_read_b128 v[220:223], v164 offset:55296
	ds_read_b128 v[224:227], v164 offset:56320
	global_load_lds_dwordx4 v140, s[98:99]
	s_add_i32 m0, s42, 0x2000
	s_add_u32 s40, s40, 0x40080
	s_addc_u32 s41, s41, 0
	s_add_i32 s42, s65, s44
	global_load_lds_dwordx4 v144, s[98:99]
	s_mov_b32 m0, s42
	s_nop 0
	global_load_lds_dwordx4 v140, s[40:41]
	s_add_i32 m0, s42, 0x2000
	s_nop 0
	global_load_lds_dwordx4 v144, s[40:41]
	s_mov_b32 m0, s50
	s_nop 0
	global_load_lds_dwordx4 v138, s[100:101]
	s_mov_b32 m0, s51
	s_nop 0
	global_load_lds_dwordx4 v142, s[100:101]
	s_waitcnt vmcnt(8)
	s_waitcnt lgkmcnt(0)
	s_setprio 1
	s_barrier
	v_mfma_f32_16x16x32_bf16 v[62:65], v[130:133], v[196:199], v[62:65]
	v_mfma_f32_16x16x32_bf16 v[58:61], v[154:157], v[196:199], v[58:61]
	v_mfma_f32_16x16x32_bf16 v[46:49], v[130:133], v[204:207], v[46:49]
	v_mfma_f32_16x16x32_bf16 v[42:45], v[154:157], v[204:207], v[42:45]
	v_mfma_f32_16x16x32_bf16 v[30:33], v[130:133], v[212:215], v[30:33]
	v_mfma_f32_16x16x32_bf16 v[26:29], v[154:157], v[212:215], v[26:29]
	v_mfma_f32_16x16x32_bf16 v[14:17], v[130:133], v[220:223], v[14:17]
	v_mfma_f32_16x16x32_bf16 v[10:13], v[154:157], v[220:223], v[10:13]
	v_mfma_f32_16x16x32_bf16 v[62:65], v[134:137], v[200:203], v[62:65]
	v_mfma_f32_16x16x32_bf16 v[58:61], v[166:169], v[200:203], v[58:61]
	v_mfma_f32_16x16x32_bf16 v[46:49], v[134:137], v[208:211], v[46:49]
	v_mfma_f32_16x16x32_bf16 v[42:45], v[166:169], v[208:211], v[42:45]
	v_mfma_f32_16x16x32_bf16 v[30:33], v[134:137], v[216:219], v[30:33]
	v_mfma_f32_16x16x32_bf16 v[26:29], v[166:169], v[216:219], v[26:29]
	v_mfma_f32_16x16x32_bf16 v[14:17], v[134:137], v[224:227], v[14:17]
	v_mfma_f32_16x16x32_bf16 v[10:13], v[166:169], v[224:227], v[10:13]
	v_mfma_f32_16x16x32_bf16 v[54:57], v[174:177], v[196:199], v[54:57]
	v_mfma_f32_16x16x32_bf16 v[50:53], v[182:185], v[196:199], v[50:53]
	v_mfma_f32_16x16x32_bf16 v[38:41], v[174:177], v[204:207], v[38:41]
	v_mfma_f32_16x16x32_bf16 v[34:37], v[182:185], v[204:207], v[34:37]
	v_mfma_f32_16x16x32_bf16 v[22:25], v[174:177], v[212:215], v[22:25]
	v_mfma_f32_16x16x32_bf16 v[18:21], v[182:185], v[212:215], v[18:21]
	v_mfma_f32_16x16x32_bf16 v[6:9], v[174:177], v[220:223], v[6:9]
	v_mfma_f32_16x16x32_bf16 v[2:5], v[182:185], v[220:223], v[2:5]
	v_mfma_f32_16x16x32_bf16 v[54:57], v[178:181], v[200:203], v[54:57]
	v_mfma_f32_16x16x32_bf16 v[50:53], v[186:189], v[200:203], v[50:53]
	v_mfma_f32_16x16x32_bf16 v[38:41], v[178:181], v[208:211], v[38:41]
	v_mfma_f32_16x16x32_bf16 v[34:37], v[186:189], v[208:211], v[34:37]
	v_mfma_f32_16x16x32_bf16 v[22:25], v[178:181], v[216:219], v[22:25]
	v_mfma_f32_16x16x32_bf16 v[18:21], v[186:189], v[216:219], v[18:21]
	v_mfma_f32_16x16x32_bf16 v[6:9], v[178:181], v[224:227], v[6:9]
	v_mfma_f32_16x16x32_bf16 v[2:5], v[186:189], v[224:227], v[2:5]
	s_barrier
	s_setprio 0
	s_add_i32 s63, s63, 2
	s_add_u32 s38, s38, 0x100
	s_addc_u32 s39, s39, 0
	s_add_u32 s61, s61, 0x100
	s_addc_u32 s62, s62, 0
	s_cmp_gt_u32 s63, 13
	s_cbranch_scc0 .LBB0_785
	s_and_b64 vcc, exec, s[14:15]
	s_cbranch_vccz .LBB0_788
	s_barrier

; #define PG8_STAGE(bufoff, gbase, voff) do { _Pragma("unroll") for (int _i = 0; _i < 2; ++_i) \
;         __builtin_amdgcn_global_load_lds((const unsigned*)((const char*)(gbase) + (voff)[_i]), (LAS unsigned*)(lds + (bufoff) + ldsw + _i * 8192), 16, 0, 0); } while (0)
; #define PG8_LDA(dst, b, h) do { _Pragma("unroll") for (int m = 0; m < 4; ++m) _Pragma("unroll") for (int k = 0; k < 2; ++k) dst[m][k] = *(const LAS bf16x8*)(lds + PG8_SA(b, h) + aoff + m * 2048 + k * 1024); } while (0)
; #define PG8_LDB(dst, b, h) do { _Pragma("unroll") for (int n = 0; n < 2; ++n) _Pragma("unroll") for (int k = 0; k < 2; ++k) dst[n][k] = *(const LAS bf16x8*)(lds + PG8_SB(b, h) + boff + n * 2048 + k * 1024); } while (0)
; #define PG8_MMA(ai, bj, At, Bt) do { __builtin_amdgcn_s_setprio(1); _Pragma("unroll") for (int m = 0; m < 4; ++m) _Pragma("unroll") for (int n = 0; n < 2; ++n) _Pragma("unroll") for (int k = 0; k < 2; ++k) \
;         acc[ai][bj][m][n] = __builtin_amdgcn_mfma_f32_16x16x32_bf16(Bt[n][k], At[m][k], acc[ai][bj][m][n], 0, 0, 0); __builtin_amdgcn_s_setprio(0); } while (0)
; #define PG8_WAIT_V(n) asm volatile("s_waitcnt vmcnt(" #n ")" ::: "memory")
; #define PG8_WAIT_L(n) asm volatile("s_waitcnt lgkmcnt(" #n ")" ::: "memory")
; #define PG8_BAR __builtin_amdgcn_s_barrier()
; template <class Epi>
; __device__ __forceinline__ void gemm_phase(LAS unsigned char* lds, const Gemm g, const StaticOrder& S, const Epi& E) {
;     ...
;         for (int t = 0; t < nt; t += 2) {
;             const bool last = (t == nt - 2);
;             const char* a1 = cA + (size_t)(t + 1) * kstep;
;             const char* a2 = last ? nA : cA + (size_t)(t + 2) * kstep; const char* b2 = last ? nB : cB + (size_t)(t + 2) * kstep;
;             const char* a3 = a2 + kstep; const char* b3 = b2 + kstep;
;             if constexpr (Epi::MIDK > 0) { if (t == Epi::MIDK) E.mid(acc, cur, wr, wc, fr, fq); }
;             PG8_LDB(B0, 0, 0); PG8_LDB(B1, 0, 1); PG8_SCHED; PG8_LDA(At, 0, 0); PG8_STAGE(PG8_SA(1, 1), a1 + hstep, voffA);
;             PG8_WAIT_V(8); PG8_WAIT_L(0); PG8_BAR; PG8_MMA(0, 0, At, B0); PG8_MMA(0, 1, At, B1); PG8_BAR; PG8_SCHED;
;             PG8_LDA(At, 0, 1); PG8_STAGE(PG8_SB(0, 0), b2, voffB); PG8_STAGE(PG8_SB(0, 1), b2 + hstep, voffB); PG8_STAGE(PG8_SA(0, 0), a2, voffA);
;             PG8_WAIT_V(8); PG8_WAIT_L(0); PG8_BAR; PG8_MMA(1, 0, At, B0); PG8_MMA(1, 1, At, B1); PG8_BAR; PG8_SCHED;
.LBB0_884:
	ds_read_b128 v[158:161], v150
	ds_read_b128 v[162:165], v150 offset:1024
	ds_read_b128 v[166:169], v150 offset:2048
	ds_read_b128 v[174:177], v150 offset:3072
	ds_read_b128 v[178:181], v151
	ds_read_b128 v[182:185], v151 offset:1024
	ds_read_b128 v[186:189], v151 offset:2048
	ds_read_b128 v[190:193], v151 offset:3072
	s_add_u32 s46, s44, 0xfffc0080
	s_addc_u32 s47, s45, -1
	s_cmp_eq_u32 s67, 12
	s_cselect_b32 s49, s62, s47
	s_cselect_b32 s48, s63, s46
	s_cselect_b32 s47, s23, s66
	s_cselect_b32 s46, s64, s65
	s_add_i32 m0, s41, 0xc000
	ds_read_b128 v[200:203], v152
	ds_read_b128 v[204:207], v152 offset:1024
	ds_read_b128 v[208:211], v152 offset:2048
	ds_read_b128 v[212:215], v152 offset:3072
	ds_read_b128 v[216:219], v152 offset:4096
	ds_read_b128 v[220:223], v152 offset:5120
	ds_read_b128 v[224:227], v152 offset:6144
	ds_read_b128 v[228:231], v152 offset:7168
	global_load_lds_dwordx4 v140, s[44:45]
	s_add_i32 m0, s41, 0xe000
	s_nop 0
	global_load_lds_dwordx4 v142, s[44:45]
	s_waitcnt vmcnt(8)
	s_waitcnt lgkmcnt(0)
	s_setprio 1
	s_barrier
	v_mfma_f32_16x16x32_bf16 v[126:129], v[158:161], v[200:203], v[126:129]
	v_mfma_f32_16x16x32_bf16 v[118:121], v[166:169], v[200:203], v[118:121]
	v_mfma_f32_16x16x32_bf16 v[110:113], v[158:161], v[208:211], v[110:113]
	v_mfma_f32_16x16x32_bf16 v[102:105], v[166:169], v[208:211], v[102:105]
	v_mfma_f32_16x16x32_bf16 v[94:97], v[158:161], v[216:219], v[94:97]
	v_mfma_f32_16x16x32_bf16 v[86:89], v[166:169], v[216:219], v[86:89]
	v_mfma_f32_16x16x32_bf16 v[78:81], v[158:161], v[224:227], v[78:81]
	v_mfma_f32_16x16x32_bf16 v[70:73], v[166:169], v[224:227], v[70:73]
	v_mfma_f32_16x16x32_bf16 v[126:129], v[162:165], v[204:207], v[126:129]
	v_mfma_f32_16x16x32_bf16 v[118:121], v[174:177], v[204:207], v[118:121]
	v_mfma_f32_16x16x32_bf16 v[110:113], v[162:165], v[212:215], v[110:113]
	v_mfma_f32_16x16x32_bf16 v[102:105], v[174:177], v[212:215], v[102:105]
	v_mfma_f32_16x16x32_bf16 v[94:97], v[162:165], v[220:223], v[94:97]
	v_mfma_f32_16x16x32_bf16 v[86:89], v[174:177], v[220:223], v[86:89]
	v_mfma_f32_16x16x32_bf16 v[78:81], v[162:165], v[228:231], v[78:81]
	v_mfma_f32_16x16x32_bf16 v[70:73], v[174:177], v[228:231], v[70:73]
	v_mfma_f32_16x16x32_bf16 v[122:125], v[178:181], v[200:203], v[122:125]
	v_mfma_f32_16x16x32_bf16 v[114:117], v[186:189], v[200:203], v[114:117]
	v_mfma_f32_16x16x32_bf16 v[106:109], v[178:181], v[208:211], v[106:109]
	v_mfma_f32_16x16x32_bf16 v[98:101], v[186:189], v[208:211], v[98:101]
	v_mfma_f32_16x16x32_bf16 v[90:93], v[178:181], v[216:219], v[90:93]
	v_mfma_f32_16x16x32_bf16 v[82:85], v[186:189], v[216:219], v[82:85]
	v_mfma_f32_16x16x32_bf16 v[74:77], v[178:181], v[224:227], v[74:77]
	v_mfma_f32_16x16x32_bf16 v[66:69], v[186:189], v[224:227], v[66:69]
	v_mfma_f32_16x16x32_bf16 v[122:125], v[182:185], v[204:207], v[122:125]
	v_mfma_f32_16x16x32_bf16 v[114:117], v[190:193], v[204:207], v[114:117]
	v_mfma_f32_16x16x32_bf16 v[106:109], v[182:185], v[212:215], v[106:109]
	v_mfma_f32_16x16x32_bf16 v[98:101], v[190:193], v[212:215], v[98:101]
	v_mfma_f32_16x16x32_bf16 v[90:93], v[182:185], v[220:223], v[90:93]
	v_mfma_f32_16x16x32_bf16 v[82:85], v[190:193], v[220:223], v[82:85]
	v_mfma_f32_16x16x32_bf16 v[74:77], v[182:185], v[228:231], v[74:77]
	v_mfma_f32_16x16x32_bf16 v[66:69], v[190:193], v[228:231], v[66:69]
	s_barrier
	s_setprio 0
	s_add_u32 s98, s46, s8
	s_addc_u32 s99, s47, s9
	s_add_u32 s100, s48, s8
	s_addc_u32 s101, s49, s9
	s_add_i32 s68, s58, s6
	s_mov_b32 m0, s68
	ds_read_b128 v[200:203], v152 offset:16384
	ds_read_b128 v[204:207], v152 offset:17408
	ds_read_b128 v[208:211], v152 offset:18432
	ds_read_b128 v[212:215], v152 offset:19456
	ds_read_b128 v[216:219], v152 offset:20480
	ds_read_b128 v[220:223], v152 offset:21504
	ds_read_b128 v[224:227], v152 offset:22528
	ds_read_b128 v[228:231], v152 offset:23552
	global_load_lds_dwordx4 v132, s[46:47]
	s_add_i32 m0, s68, 0x2000
	s_add_u32 s68, s46, 0x40000
	s_addc_u32 s69, s47, 0
	s_add_i32 s76, s59, s6
	global_load_lds_dwordx4 v136, s[46:47]
	s_mov_b32 m0, s76
	s_nop 0
	global_load_lds_dwordx4 v132, s[68:69]
	s_add_i32 m0, s76, 0x2000
	s_nop 0
	global_load_lds_dwordx4 v136, s[68:69]
	s_mov_b32 m0, s41
	s_nop 0
	global_load_lds_dwordx4 v130, s[48:49]
	s_mov_b32 m0, s43
	s_nop 0
	global_load_lds_dwordx4 v134, s[48:49]
	s_waitcnt vmcnt(8)
	s_waitcnt lgkmcnt(0)
	s_setprio 1
	s_barrier
	v_mfma_f32_16x16x32_bf16 v[62:65], v[158:161], v[200:203], v[62:65]
	v_mfma_f32_16x16x32_bf16 v[54:57], v[166:169], v[200:203], v[54:57]
	v_mfma_f32_16x16x32_bf16 v[46:49], v[158:161], v[208:211], v[46:49]
	v_mfma_f32_16x16x32_bf16 v[38:41], v[166:169], v[208:211], v[38:41]
	v_mfma_f32_16x16x32_bf16 v[30:33], v[158:161], v[216:219], v[30:33]
	v_mfma_f32_16x16x32_bf16 v[22:25], v[166:169], v[216:219], v[22:25]
	v_mfma_f32_16x16x32_bf16 v[14:17], v[158:161], v[224:227], v[14:17]
	v_mfma_f32_16x16x32_bf16 v[6:9], v[166:169], v[224:227], v[6:9]
	v_mfma_f32_16x16x32_bf16 v[62:65], v[162:165], v[204:207], v[62:65]
	v_mfma_f32_16x16x32_bf16 v[54:57], v[174:177], v[204:207], v[54:57]
	v_mfma_f32_16x16x32_bf16 v[46:49], v[162:165], v[212:215], v[46:49]
	v_mfma_f32_16x16x32_bf16 v[38:41], v[174:177], v[212:215], v[38:41]
	v_mfma_f32_16x16x32_bf16 v[30:33], v[162:165], v[220:223], v[30:33]
	v_mfma_f32_16x16x32_bf16 v[22:25], v[174:177], v[220:223], v[22:25]
	v_mfma_f32_16x16x32_bf16 v[14:17], v[162:165], v[228:231], v[14:17]
	v_mfma_f32_16x16x32_bf16 v[6:9], v[174:177], v[228:231], v[6:9]
	v_mfma_f32_16x16x32_bf16 v[58:61], v[178:181], v[200:203], v[58:61]
	v_mfma_f32_16x16x32_bf16 v[50:53], v[186:189], v[200:203], v[50:53]
	v_mfma_f32_16x16x32_bf16 v[42:45], v[178:181], v[208:211], v[42:45]
	v_mfma_f32_16x16x32_bf16 v[34:37], v[186:189], v[208:211], v[34:37]
	v_mfma_f32_16x16x32_bf16 v[26:29], v[178:181], v[216:219], v[26:29]
	v_mfma_f32_16x16x32_bf16 v[18:21], v[186:189], v[216:219], v[18:21]
	v_mfma_f32_16x16x32_bf16 v[10:13], v[178:181], v[224:227], v[10:13]
	v_mfma_f32_16x16x32_bf16 v[2:5], v[186:189], v[224:227], v[2:5]
	v_mfma_f32_16x16x32_bf16 v[58:61], v[182:185], v[204:207], v[58:61]
	v_mfma_f32_16x16x32_bf16 v[50:53], v[190:193], v[204:207], v[50:53]
	v_mfma_f32_16x16x32_bf16 v[42:45], v[182:185], v[212:215], v[42:45]
	v_mfma_f32_16x16x32_bf16 v[34:37], v[190:193], v[212:215], v[34:37]
	v_mfma_f32_16x16x32_bf16 v[26:29], v[182:185], v[220:223], v[26:29]
	v_mfma_f32_16x16x32_bf16 v[18:21], v[190:193], v[220:223], v[18:21]
	v_mfma_f32_16x16x32_bf16 v[10:13], v[182:185], v[228:231], v[10:13]
	v_mfma_f32_16x16x32_bf16 v[2:5], v[190:193], v[228:231], v[2:5]
	s_barrier
; #define PG8_STAGE(bufoff, gbase, voff) do { _Pragma("unroll") for (int _i = 0; _i < 2; ++_i) \
;         __builtin_amdgcn_global_load_lds((const unsigned*)((const char*)(gbase) + (voff)[_i]), (LAS unsigned*)(lds + (bufoff) + ldsw + _i * 8192), 16, 0, 0); } while (0)
; #define PG8_LDA(dst, b, h) do { _Pragma("unroll") for (int m = 0; m < 4; ++m) _Pragma("unroll") for (int k = 0; k < 2; ++k) dst[m][k] = *(const LAS bf16x8*)(lds + PG8_SA(b, h) + aoff + m * 2048 + k * 1024); } while (0)
; #define PG8_LDB(dst, b, h) do { _Pragma("unroll") for (int n = 0; n < 2; ++n) _Pragma("unroll") for (int k = 0; k < 2; ++k) dst[n][k] = *(const LAS bf16x8*)(lds + PG8_SB(b, h) + boff + n * 2048 + k * 1024); } while (0)
; #define PG8_MMA(ai, bj, At, Bt) do { __builtin_amdgcn_s_setprio(1); _Pragma("unroll") for (int m = 0; m < 4; ++m) _Pragma("unroll") for (int n = 0; n < 2; ++n) _Pragma("unroll") for (int k = 0; k < 2; ++k) \
;         acc[ai][bj][m][n] = __builtin_amdgcn_mfma_f32_16x16x32_bf16(Bt[n][k], At[m][k], acc[ai][bj][m][n], 0, 0, 0); __builtin_amdgcn_s_setprio(0); } while (0)
; #define PG8_WAIT_V(n) asm volatile("s_waitcnt vmcnt(" #n ")" ::: "memory")
; #define PG8_WAIT_L(n) asm volatile("s_waitcnt lgkmcnt(" #n ")" ::: "memory")
; #define PG8_BAR __builtin_amdgcn_s_barrier()
; #define PG8_SCHED __builtin_amdgcn_sched_barrier(0)
; template <class Epi>
; __device__ __forceinline__ void gemm_phase(LAS unsigned char* lds, const Gemm g, const StaticOrder& S, const Epi& E) {
;     ...
;         for (int t = 0; t < nt; t += 2) {
;     ...
;             PG8_LDB(B0, 1, 0); PG8_LDB(B1, 1, 1); PG8_SCHED; PG8_LDA(At, 1, 0); PG8_STAGE(PG8_SA(0, 1), a2 + hstep, voffA);
;             PG8_WAIT_V(8); PG8_WAIT_L(0); PG8_BAR; PG8_MMA(0, 0, At, B0); PG8_MMA(0, 1, At, B1); PG8_BAR; PG8_SCHED;
;             PG8_LDA(At, 1, 1); PG8_STAGE(PG8_SB(1, 0), b3, voffB); PG8_STAGE(PG8_SB(1, 1), b3 + hstep, voffB); PG8_STAGE(PG8_SA(1, 0), a3, voffA);
;             PG8_WAIT_V(8); PG8_WAIT_L(0); PG8_BAR; PG8_MMA(1, 0, At, B0); PG8_MMA(1, 1, At, B1); PG8_BAR; PG8_SCHED;
;         }
;         if (wr == 0) PG8_BAR;
	s_setprio 0
	s_add_i32 s68, 0, 0x18000
	s_add_i32 s69, 0, 0x1c000
	v_add_u32_e32 v174, s68, v148
	v_add_u32_e32 v190, s69, v148
	ds_read_b128 v[158:161], v174
	ds_read_b128 v[162:165], v174 offset:1024
	ds_read_b128 v[166:169], v174 offset:2048
	ds_read_b128 v[174:177], v174 offset:3072
	ds_read_b128 v[178:181], v190
	ds_read_b128 v[182:185], v190 offset:1024
	ds_read_b128 v[186:189], v190 offset:2048
	ds_read_b128 v[190:193], v190 offset:3072
	s_add_u32 s48, s48, 0x40000
	s_addc_u32 s49, s49, 0
	s_mov_b32 m0, s51
	ds_read_b128 v[200:203], v152 offset:32768
	ds_read_b128 v[204:207], v152 offset:33792
	ds_read_b128 v[208:211], v152 offset:34816
	ds_read_b128 v[212:215], v152 offset:35840
	ds_read_b128 v[216:219], v152 offset:36864
	ds_read_b128 v[220:223], v152 offset:37888
	ds_read_b128 v[224:227], v152 offset:38912
	ds_read_b128 v[228:231], v152 offset:39936
	global_load_lds_dwordx4 v130, s[48:49]
	s_mov_b32 m0, s52
	s_nop 0
	global_load_lds_dwordx4 v134, s[48:49]
	s_waitcnt vmcnt(8)
	s_waitcnt lgkmcnt(0)
	s_setprio 1
	s_barrier
	v_mfma_f32_16x16x32_bf16 v[126:129], v[158:161], v[200:203], v[126:129]
	v_mfma_f32_16x16x32_bf16 v[118:121], v[166:169], v[200:203], v[118:121]
	v_mfma_f32_16x16x32_bf16 v[110:113], v[158:161], v[208:211], v[110:113]
	v_mfma_f32_16x16x32_bf16 v[102:105], v[166:169], v[208:211], v[102:105]
	v_mfma_f32_16x16x32_bf16 v[94:97], v[158:161], v[216:219], v[94:97]
	v_mfma_f32_16x16x32_bf16 v[86:89], v[166:169], v[216:219], v[86:89]
	v_mfma_f32_16x16x32_bf16 v[78:81], v[158:161], v[224:227], v[78:81]
	v_mfma_f32_16x16x32_bf16 v[70:73], v[166:169], v[224:227], v[70:73]
	v_mfma_f32_16x16x32_bf16 v[126:129], v[162:165], v[204:207], v[126:129]
	v_mfma_f32_16x16x32_bf16 v[118:121], v[174:177], v[204:207], v[118:121]
	v_mfma_f32_16x16x32_bf16 v[110:113], v[162:165], v[212:215], v[110:113]
	v_mfma_f32_16x16x32_bf16 v[102:105], v[174:177], v[212:215], v[102:105]
	v_mfma_f32_16x16x32_bf16 v[94:97], v[162:165], v[220:223], v[94:97]
	v_mfma_f32_16x16x32_bf16 v[86:89], v[174:177], v[220:223], v[86:89]
	v_mfma_f32_16x16x32_bf16 v[78:81], v[162:165], v[228:231], v[78:81]
	v_mfma_f32_16x16x32_bf16 v[70:73], v[174:177], v[228:231], v[70:73]
	v_mfma_f32_16x16x32_bf16 v[122:125], v[178:181], v[200:203], v[122:125]
	v_mfma_f32_16x16x32_bf16 v[114:117], v[186:189], v[200:203], v[114:117]
	v_mfma_f32_16x16x32_bf16 v[106:109], v[178:181], v[208:211], v[106:109]
	v_mfma_f32_16x16x32_bf16 v[98:101], v[186:189], v[208:211], v[98:101]
	v_mfma_f32_16x16x32_bf16 v[90:93], v[178:181], v[216:219], v[90:93]
	v_mfma_f32_16x16x32_bf16 v[82:85], v[186:189], v[216:219], v[82:85]
	v_mfma_f32_16x16x32_bf16 v[74:77], v[178:181], v[224:227], v[74:77]
	v_mfma_f32_16x16x32_bf16 v[66:69], v[186:189], v[224:227], v[66:69]
	v_mfma_f32_16x16x32_bf16 v[122:125], v[182:185], v[204:207], v[122:125]
	v_mfma_f32_16x16x32_bf16 v[114:117], v[190:193], v[204:207], v[114:117]
	v_mfma_f32_16x16x32_bf16 v[106:109], v[182:185], v[212:215], v[106:109]
	v_mfma_f32_16x16x32_bf16 v[98:101], v[190:193], v[212:215], v[98:101]
	v_mfma_f32_16x16x32_bf16 v[90:93], v[182:185], v[220:223], v[90:93]
	v_mfma_f32_16x16x32_bf16 v[82:85], v[190:193], v[220:223], v[82:85]
	v_mfma_f32_16x16x32_bf16 v[74:77], v[182:185], v[228:231], v[74:77]
	v_mfma_f32_16x16x32_bf16 v[66:69], v[190:193], v[228:231], v[66:69]
	s_barrier
	s_setprio 0
	s_add_i32 s48, s68, s6
	s_mov_b32 m0, s48
	ds_read_b128 v[200:203], v152 offset:49152
	ds_read_b128 v[204:207], v152 offset:50176
	ds_read_b128 v[208:211], v152 offset:51200
	ds_read_b128 v[212:215], v152 offset:52224
	ds_read_b128 v[216:219], v152 offset:53248
	ds_read_b128 v[220:223], v152 offset:54272
	ds_read_b128 v[224:227], v152 offset:55296
	ds_read_b128 v[228:231], v152 offset:56320
	global_load_lds_dwordx4 v132, s[98:99]
	s_add_i32 m0, s48, 0x2000
	s_add_u32 s46, s46, 0x40080
	s_addc_u32 s47, s47, 0
	s_add_i32 s48, s69, s6
	global_load_lds_dwordx4 v136, s[98:99]
	s_mov_b32 m0, s48
	s_nop 0
	global_load_lds_dwordx4 v132, s[46:47]
	s_add_i32 m0, s48, 0x2000
	s_nop 0
	global_load_lds_dwordx4 v136, s[46:47]
	s_mov_b32 m0, s53
	s_nop 0
	global_load_lds_dwordx4 v130, s[100:101]
	s_mov_b32 m0, s54
	s_nop 0
	global_load_lds_dwordx4 v134, s[100:101]
	s_waitcnt vmcnt(8)
	s_waitcnt lgkmcnt(0)
	s_setprio 1
	s_barrier
	v_mfma_f32_16x16x32_bf16 v[62:65], v[158:161], v[200:203], v[62:65]
	v_mfma_f32_16x16x32_bf16 v[54:57], v[166:169], v[200:203], v[54:57]
	v_mfma_f32_16x16x32_bf16 v[46:49], v[158:161], v[208:211], v[46:49]
	v_mfma_f32_16x16x32_bf16 v[38:41], v[166:169], v[208:211], v[38:41]
	v_mfma_f32_16x16x32_bf16 v[30:33], v[158:161], v[216:219], v[30:33]
	v_mfma_f32_16x16x32_bf16 v[22:25], v[166:169], v[216:219], v[22:25]
	v_mfma_f32_16x16x32_bf16 v[14:17], v[158:161], v[224:227], v[14:17]
	v_mfma_f32_16x16x32_bf16 v[6:9], v[166:169], v[224:227], v[6:9]
	v_mfma_f32_16x16x32_bf16 v[62:65], v[162:165], v[204:207], v[62:65]
	v_mfma_f32_16x16x32_bf16 v[54:57], v[174:177], v[204:207], v[54:57]
	v_mfma_f32_16x16x32_bf16 v[46:49], v[162:165], v[212:215], v[46:49]
	v_mfma_f32_16x16x32_bf16 v[38:41], v[174:177], v[212:215], v[38:41]
	v_mfma_f32_16x16x32_bf16 v[30:33], v[162:165], v[220:223], v[30:33]
	v_mfma_f32_16x16x32_bf16 v[22:25], v[174:177], v[220:223], v[22:25]
	v_mfma_f32_16x16x32_bf16 v[14:17], v[162:165], v[228:231], v[14:17]
	v_mfma_f32_16x16x32_bf16 v[6:9], v[174:177], v[228:231], v[6:9]
	v_mfma_f32_16x16x32_bf16 v[58:61], v[178:181], v[200:203], v[58:61]
	v_mfma_f32_16x16x32_bf16 v[50:53], v[186:189], v[200:203], v[50:53]
	v_mfma_f32_16x16x32_bf16 v[42:45], v[178:181], v[208:211], v[42:45]
	v_mfma_f32_16x16x32_bf16 v[34:37], v[186:189], v[208:211], v[34:37]
	v_mfma_f32_16x16x32_bf16 v[26:29], v[178:181], v[216:219], v[26:29]
	v_mfma_f32_16x16x32_bf16 v[18:21], v[186:189], v[216:219], v[18:21]
	v_mfma_f32_16x16x32_bf16 v[10:13], v[178:181], v[224:227], v[10:13]
	v_mfma_f32_16x16x32_bf16 v[2:5], v[186:189], v[224:227], v[2:5]
	v_mfma_f32_16x16x32_bf16 v[58:61], v[182:185], v[204:207], v[58:61]
	v_mfma_f32_16x16x32_bf16 v[50:53], v[190:193], v[204:207], v[50:53]
	v_mfma_f32_16x16x32_bf16 v[42:45], v[182:185], v[212:215], v[42:45]
	v_mfma_f32_16x16x32_bf16 v[34:37], v[190:193], v[212:215], v[34:37]
	v_mfma_f32_16x16x32_bf16 v[26:29], v[182:185], v[220:223], v[26:29]
	v_mfma_f32_16x16x32_bf16 v[18:21], v[190:193], v[220:223], v[18:21]
	v_mfma_f32_16x16x32_bf16 v[10:13], v[182:185], v[228:231], v[10:13]
	v_mfma_f32_16x16x32_bf16 v[2:5], v[190:193], v[228:231], v[2:5]
	s_barrier
	s_setprio 0
	s_add_i32 s67, s67, 2
	s_add_u32 s44, s44, 0x100
	s_addc_u32 s45, s45, 0
	s_add_u32 s65, s65, 0x100
	s_addc_u32 s66, s66, 0
	s_cmp_gt_u32 s67, 13
	s_cbranch_scc0 .LBB0_884
	s_and_b64 vcc, exec, s[14:15]
	s_cbranch_vccz .LBB0_887
	s_barrier

; #define PG8_STAGE(bufoff, gbase, voff) do { _Pragma("unroll") for (int _i = 0; _i < 2; ++_i) \
;         __builtin_amdgcn_global_load_lds((const unsigned*)((const char*)(gbase) + (voff)[_i]), (LAS unsigned*)(lds + (bufoff) + ldsw + _i * 8192), 16, 0, 0); } while (0)
; #define PG8_LDA(dst, b, h) do { _Pragma("unroll") for (int m = 0; m < 4; ++m) _Pragma("unroll") for (int k = 0; k < 2; ++k) dst[m][k] = *(const LAS bf16x8*)(lds + PG8_SA(b, h) + aoff + m * 2048 + k * 1024); } while (0)
; #define PG8_LDB(dst, b, h) do { _Pragma("unroll") for (int n = 0; n < 2; ++n) _Pragma("unroll") for (int k = 0; k < 2; ++k) dst[n][k] = *(const LAS bf16x8*)(lds + PG8_SB(b, h) + boff + n * 2048 + k * 1024); } while (0)
; #define PG8_MMA(ai, bj, At, Bt) do { __builtin_amdgcn_s_setprio(1); _Pragma("unroll") for (int m = 0; m < 4; ++m) _Pragma("unroll") for (int n = 0; n < 2; ++n) _Pragma("unroll") for (int k = 0; k < 2; ++k) \
;         acc[ai][bj][m][n] = __builtin_amdgcn_mfma_f32_16x16x32_bf16(Bt[n][k], At[m][k], acc[ai][bj][m][n], 0, 0, 0); __builtin_amdgcn_s_setprio(0); } while (0)
; #define PG8_WAIT_V(n) asm volatile("s_waitcnt vmcnt(" #n ")" ::: "memory")
; #define PG8_WAIT_L(n) asm volatile("s_waitcnt lgkmcnt(" #n ")" ::: "memory")
; #define PG8_BAR __builtin_amdgcn_s_barrier()
; template <class Epi>
; __device__ __forceinline__ void gemm_phase(LAS unsigned char* lds, const Gemm g, const StaticOrder& S, const Epi& E) {
;     ...
;         for (int t = 0; t < nt; t += 2) {
;             const bool last = (t == nt - 2);
;             const char* a1 = cA + (size_t)(t + 1) * kstep;
;             const char* a2 = last ? nA : cA + (size_t)(t + 2) * kstep; const char* b2 = last ? nB : cB + (size_t)(t + 2) * kstep;
;             const char* a3 = a2 + kstep; const char* b3 = b2 + kstep;
;             if constexpr (Epi::MIDK > 0) { if (t == Epi::MIDK) E.mid(acc, cur, wr, wc, fr, fq); }
;             PG8_LDB(B0, 0, 0); PG8_LDB(B1, 0, 1); PG8_SCHED; PG8_LDA(At, 0, 0); PG8_STAGE(PG8_SA(1, 1), a1 + hstep, voffA);
;             PG8_WAIT_V(8); PG8_WAIT_L(0); PG8_BAR; PG8_MMA(0, 0, At, B0); PG8_MMA(0, 1, At, B1); PG8_BAR; PG8_SCHED;
;             PG8_LDA(At, 0, 1); PG8_STAGE(PG8_SB(0, 0), b2, voffB); PG8_STAGE(PG8_SB(0, 1), b2 + hstep, voffB); PG8_STAGE(PG8_SA(0, 0), a2, voffA);
;             PG8_WAIT_V(8); PG8_WAIT_L(0); PG8_BAR; PG8_MMA(1, 0, At, B0); PG8_MMA(1, 1, At, B1); PG8_BAR; PG8_SCHED;
.LBB0_971:
	ds_read_b128 v[130:133], v162
	ds_read_b128 v[134:137], v162 offset:1024
	ds_read_b128 v[154:157], v162 offset:2048
	ds_read_b128 v[166:169], v162 offset:3072
	ds_read_b128 v[174:177], v163
	ds_read_b128 v[178:181], v163 offset:1024
	ds_read_b128 v[182:185], v163 offset:2048
	ds_read_b128 v[186:189], v163 offset:3072
	s_add_u32 s24, s22, 0xfff50080
	s_addc_u32 s25, s23, -1
	s_cmp_eq_u32 s59, 40
	s_cselect_b32 s27, s5, s25
	s_cselect_b32 s26, s4, s24
	s_cselect_b32 s25, s21, s58
	s_cselect_b32 s24, s20, s57
	s_add_i32 m0, s39, 0xc000
	ds_read_b128 v[196:199], v164
	ds_read_b128 v[200:203], v164 offset:1024
	ds_read_b128 v[204:207], v164 offset:2048
	ds_read_b128 v[208:211], v164 offset:3072
	ds_read_b128 v[212:215], v164 offset:4096
	ds_read_b128 v[216:219], v164 offset:5120
	ds_read_b128 v[220:223], v164 offset:6144
	ds_read_b128 v[224:227], v164 offset:7168
	global_load_lds_dwordx4 v146, s[22:23]
	s_add_i32 m0, s39, 0xe000
	s_nop 0
	global_load_lds_dwordx4 v148, s[22:23]
	s_waitcnt vmcnt(8)
	s_waitcnt lgkmcnt(0)
	s_setprio 1
	s_barrier
	v_mfma_f32_16x16x32_bf16 v[126:129], v[130:133], v[196:199], v[126:129]
	v_mfma_f32_16x16x32_bf16 v[122:125], v[154:157], v[196:199], v[122:125]
	v_mfma_f32_16x16x32_bf16 v[110:113], v[130:133], v[204:207], v[110:113]
	v_mfma_f32_16x16x32_bf16 v[106:109], v[154:157], v[204:207], v[106:109]
	v_mfma_f32_16x16x32_bf16 v[94:97], v[130:133], v[212:215], v[94:97]
	v_mfma_f32_16x16x32_bf16 v[90:93], v[154:157], v[212:215], v[90:93]
	v_mfma_f32_16x16x32_bf16 v[78:81], v[130:133], v[220:223], v[78:81]
	v_mfma_f32_16x16x32_bf16 v[74:77], v[154:157], v[220:223], v[74:77]
	v_mfma_f32_16x16x32_bf16 v[126:129], v[134:137], v[200:203], v[126:129]
	v_mfma_f32_16x16x32_bf16 v[122:125], v[166:169], v[200:203], v[122:125]
	v_mfma_f32_16x16x32_bf16 v[110:113], v[134:137], v[208:211], v[110:113]
	v_mfma_f32_16x16x32_bf16 v[106:109], v[166:169], v[208:211], v[106:109]
	v_mfma_f32_16x16x32_bf16 v[94:97], v[134:137], v[216:219], v[94:97]
	v_mfma_f32_16x16x32_bf16 v[90:93], v[166:169], v[216:219], v[90:93]
	v_mfma_f32_16x16x32_bf16 v[78:81], v[134:137], v[224:227], v[78:81]
	v_mfma_f32_16x16x32_bf16 v[74:77], v[166:169], v[224:227], v[74:77]
	v_mfma_f32_16x16x32_bf16 v[118:121], v[174:177], v[196:199], v[118:121]
	v_mfma_f32_16x16x32_bf16 v[114:117], v[182:185], v[196:199], v[114:117]
	v_mfma_f32_16x16x32_bf16 v[102:105], v[174:177], v[204:207], v[102:105]
	v_mfma_f32_16x16x32_bf16 v[98:101], v[182:185], v[204:207], v[98:101]
	v_mfma_f32_16x16x32_bf16 v[86:89], v[174:177], v[212:215], v[86:89]
	v_mfma_f32_16x16x32_bf16 v[82:85], v[182:185], v[212:215], v[82:85]
	v_mfma_f32_16x16x32_bf16 v[70:73], v[174:177], v[220:223], v[70:73]
	v_mfma_f32_16x16x32_bf16 v[66:69], v[182:185], v[220:223], v[66:69]
	v_mfma_f32_16x16x32_bf16 v[118:121], v[178:181], v[200:203], v[118:121]
	v_mfma_f32_16x16x32_bf16 v[114:117], v[186:189], v[200:203], v[114:117]
	v_mfma_f32_16x16x32_bf16 v[102:105], v[178:181], v[208:211], v[102:105]
	v_mfma_f32_16x16x32_bf16 v[98:101], v[186:189], v[208:211], v[98:101]
	v_mfma_f32_16x16x32_bf16 v[86:89], v[178:181], v[216:219], v[86:89]
	v_mfma_f32_16x16x32_bf16 v[82:85], v[186:189], v[216:219], v[82:85]
	v_mfma_f32_16x16x32_bf16 v[70:73], v[178:181], v[224:227], v[70:73]
	v_mfma_f32_16x16x32_bf16 v[66:69], v[186:189], v[224:227], v[66:69]
	s_barrier
	s_setprio 0
	s_add_u32 s98, s24, s14
	s_addc_u32 s99, s25, s15
	s_add_u32 s100, s26, s14
	s_addc_u32 s101, s27, s15
	s_add_i32 s60, s51, s38
	s_mov_b32 m0, s60
	ds_read_b128 v[196:199], v164 offset:16384
	ds_read_b128 v[200:203], v164 offset:17408
	ds_read_b128 v[204:207], v164 offset:18432
	ds_read_b128 v[208:211], v164 offset:19456
	ds_read_b128 v[212:215], v164 offset:20480
	ds_read_b128 v[216:219], v164 offset:21504
	ds_read_b128 v[220:223], v164 offset:22528
	ds_read_b128 v[224:227], v164 offset:23552
	global_load_lds_dwordx4 v140, s[24:25]
	s_add_i32 m0, s60, 0x2000
	s_add_u32 s60, s24, 0xb0000
	s_addc_u32 s61, s25, 0
	s_add_i32 s62, s52, s38
	global_load_lds_dwordx4 v144, s[24:25]
	s_mov_b32 m0, s62
	s_nop 0
	global_load_lds_dwordx4 v140, s[60:61]
	s_add_i32 m0, s62, 0x2000
	s_nop 0
	global_load_lds_dwordx4 v144, s[60:61]
	s_mov_b32 m0, s39
	s_nop 0
	global_load_lds_dwordx4 v138, s[26:27]
	s_mov_b32 m0, s40
	s_nop 0
	global_load_lds_dwordx4 v142, s[26:27]
	s_waitcnt vmcnt(8)
	s_waitcnt lgkmcnt(0)
	s_setprio 1
	s_barrier
	v_mfma_f32_16x16x32_bf16 v[62:65], v[130:133], v[196:199], v[62:65]
	v_mfma_f32_16x16x32_bf16 v[58:61], v[154:157], v[196:199], v[58:61]
	v_mfma_f32_16x16x32_bf16 v[46:49], v[130:133], v[204:207], v[46:49]
	v_mfma_f32_16x16x32_bf16 v[42:45], v[154:157], v[204:207], v[42:45]
	v_mfma_f32_16x16x32_bf16 v[30:33], v[130:133], v[212:215], v[30:33]
	v_mfma_f32_16x16x32_bf16 v[26:29], v[154:157], v[212:215], v[26:29]
	v_mfma_f32_16x16x32_bf16 v[14:17], v[130:133], v[220:223], v[14:17]
	v_mfma_f32_16x16x32_bf16 v[10:13], v[154:157], v[220:223], v[10:13]
	v_mfma_f32_16x16x32_bf16 v[62:65], v[134:137], v[200:203], v[62:65]
	v_mfma_f32_16x16x32_bf16 v[58:61], v[166:169], v[200:203], v[58:61]
	v_mfma_f32_16x16x32_bf16 v[46:49], v[134:137], v[208:211], v[46:49]
	v_mfma_f32_16x16x32_bf16 v[42:45], v[166:169], v[208:211], v[42:45]
	v_mfma_f32_16x16x32_bf16 v[30:33], v[134:137], v[216:219], v[30:33]
	v_mfma_f32_16x16x32_bf16 v[26:29], v[166:169], v[216:219], v[26:29]
	v_mfma_f32_16x16x32_bf16 v[14:17], v[134:137], v[224:227], v[14:17]
	v_mfma_f32_16x16x32_bf16 v[10:13], v[166:169], v[224:227], v[10:13]
	v_mfma_f32_16x16x32_bf16 v[54:57], v[174:177], v[196:199], v[54:57]
	v_mfma_f32_16x16x32_bf16 v[50:53], v[182:185], v[196:199], v[50:53]
	v_mfma_f32_16x16x32_bf16 v[38:41], v[174:177], v[204:207], v[38:41]
	v_mfma_f32_16x16x32_bf16 v[34:37], v[182:185], v[204:207], v[34:37]
	v_mfma_f32_16x16x32_bf16 v[22:25], v[174:177], v[212:215], v[22:25]
	v_mfma_f32_16x16x32_bf16 v[18:21], v[182:185], v[212:215], v[18:21]
	v_mfma_f32_16x16x32_bf16 v[6:9], v[174:177], v[220:223], v[6:9]
	v_mfma_f32_16x16x32_bf16 v[2:5], v[182:185], v[220:223], v[2:5]
	v_mfma_f32_16x16x32_bf16 v[54:57], v[178:181], v[200:203], v[54:57]
	v_mfma_f32_16x16x32_bf16 v[50:53], v[186:189], v[200:203], v[50:53]
	v_mfma_f32_16x16x32_bf16 v[38:41], v[178:181], v[208:211], v[38:41]
	v_mfma_f32_16x16x32_bf16 v[34:37], v[186:189], v[208:211], v[34:37]
	v_mfma_f32_16x16x32_bf16 v[22:25], v[178:181], v[216:219], v[22:25]
	v_mfma_f32_16x16x32_bf16 v[18:21], v[186:189], v[216:219], v[18:21]
	v_mfma_f32_16x16x32_bf16 v[6:9], v[178:181], v[224:227], v[6:9]
	v_mfma_f32_16x16x32_bf16 v[2:5], v[186:189], v[224:227], v[2:5]
	s_barrier
; #define PG8_STAGE(bufoff, gbase, voff) do { _Pragma("unroll") for (int _i = 0; _i < 2; ++_i) \
;         __builtin_amdgcn_global_load_lds((const unsigned*)((const char*)(gbase) + (voff)[_i]), (LAS unsigned*)(lds + (bufoff) + ldsw + _i * 8192), 16, 0, 0); } while (0)
; #define PG8_LDA(dst, b, h) do { _Pragma("unroll") for (int m = 0; m < 4; ++m) _Pragma("unroll") for (int k = 0; k < 2; ++k) dst[m][k] = *(const LAS bf16x8*)(lds + PG8_SA(b, h) + aoff + m * 2048 + k * 1024); } while (0)
; #define PG8_LDB(dst, b, h) do { _Pragma("unroll") for (int n = 0; n < 2; ++n) _Pragma("unroll") for (int k = 0; k < 2; ++k) dst[n][k] = *(const LAS bf16x8*)(lds + PG8_SB(b, h) + boff + n * 2048 + k * 1024); } while (0)
; #define PG8_MMA(ai, bj, At, Bt) do { __builtin_amdgcn_s_setprio(1); _Pragma("unroll") for (int m = 0; m < 4; ++m) _Pragma("unroll") for (int n = 0; n < 2; ++n) _Pragma("unroll") for (int k = 0; k < 2; ++k) \
;         acc[ai][bj][m][n] = __builtin_amdgcn_mfma_f32_16x16x32_bf16(Bt[n][k], At[m][k], acc[ai][bj][m][n], 0, 0, 0); __builtin_amdgcn_s_setprio(0); } while (0)
; #define PG8_WAIT_V(n) asm volatile("s_waitcnt vmcnt(" #n ")" ::: "memory")
; #define PG8_WAIT_L(n) asm volatile("s_waitcnt lgkmcnt(" #n ")" ::: "memory")
; #define PG8_BAR __builtin_amdgcn_s_barrier()
; #define PG8_SCHED __builtin_amdgcn_sched_barrier(0)
; template <class Epi>
; __device__ __forceinline__ void gemm_phase(LAS unsigned char* lds, const Gemm g, const StaticOrder& S, const Epi& E) {
;     ...
;             PG8_LDB(B0, 1, 0); PG8_LDB(B1, 1, 1); PG8_SCHED; PG8_LDA(At, 1, 0); PG8_STAGE(PG8_SA(0, 1), a2 + hstep, voffA);
;             PG8_WAIT_V(8); PG8_WAIT_L(0); PG8_BAR; PG8_MMA(0, 0, At, B0); PG8_MMA(0, 1, At, B1); PG8_BAR; PG8_SCHED;
;             PG8_LDA(At, 1, 1); PG8_STAGE(PG8_SB(1, 0), b3, voffB); PG8_STAGE(PG8_SB(1, 1), b3 + hstep, voffB); PG8_STAGE(PG8_SA(1, 0), a3, voffA);
;             PG8_WAIT_V(8); PG8_WAIT_L(0); PG8_BAR; PG8_MMA(1, 0, At, B0); PG8_MMA(1, 1, At, B1); PG8_BAR; PG8_SCHED;
;         }
;         if (wr == 0) PG8_BAR;
	s_setprio 0
	s_add_i32 s60, 0, 0x18000
	s_add_i32 s61, 0, 0x1c000
	v_add_u32_e32 v166, s60, v160
	v_add_u32_e32 v186, s61, v160
	ds_read_b128 v[130:133], v166
	ds_read_b128 v[134:137], v166 offset:1024
	ds_read_b128 v[154:157], v166 offset:2048
	ds_read_b128 v[166:169], v166 offset:3072
	ds_read_b128 v[174:177], v186
	ds_read_b128 v[178:181], v186 offset:1024
	ds_read_b128 v[182:185], v186 offset:2048
	ds_read_b128 v[186:189], v186 offset:3072
	s_add_u32 s26, s26, 0xb0000
	s_addc_u32 s27, s27, 0
	s_mov_b32 m0, s41
	ds_read_b128 v[196:199], v164 offset:32768
	ds_read_b128 v[200:203], v164 offset:33792
	ds_read_b128 v[204:207], v164 offset:34816
	ds_read_b128 v[208:211], v164 offset:35840
	ds_read_b128 v[212:215], v164 offset:36864
	ds_read_b128 v[216:219], v164 offset:37888
	ds_read_b128 v[220:223], v164 offset:38912
	ds_read_b128 v[224:227], v164 offset:39936
	global_load_lds_dwordx4 v138, s[26:27]
	s_mov_b32 m0, s42
	s_nop 0
	global_load_lds_dwordx4 v142, s[26:27]
	s_waitcnt vmcnt(8)
	s_waitcnt lgkmcnt(0)
	s_setprio 1
	s_barrier
	v_mfma_f32_16x16x32_bf16 v[126:129], v[130:133], v[196:199], v[126:129]
	v_mfma_f32_16x16x32_bf16 v[122:125], v[154:157], v[196:199], v[122:125]
	v_mfma_f32_16x16x32_bf16 v[110:113], v[130:133], v[204:207], v[110:113]
	v_mfma_f32_16x16x32_bf16 v[106:109], v[154:157], v[204:207], v[106:109]
	v_mfma_f32_16x16x32_bf16 v[94:97], v[130:133], v[212:215], v[94:97]
	v_mfma_f32_16x16x32_bf16 v[90:93], v[154:157], v[212:215], v[90:93]
	v_mfma_f32_16x16x32_bf16 v[78:81], v[130:133], v[220:223], v[78:81]
	v_mfma_f32_16x16x32_bf16 v[74:77], v[154:157], v[220:223], v[74:77]
	v_mfma_f32_16x16x32_bf16 v[126:129], v[134:137], v[200:203], v[126:129]
	v_mfma_f32_16x16x32_bf16 v[122:125], v[166:169], v[200:203], v[122:125]
	v_mfma_f32_16x16x32_bf16 v[110:113], v[134:137], v[208:211], v[110:113]
	v_mfma_f32_16x16x32_bf16 v[106:109], v[166:169], v[208:211], v[106:109]
	v_mfma_f32_16x16x32_bf16 v[94:97], v[134:137], v[216:219], v[94:97]
	v_mfma_f32_16x16x32_bf16 v[90:93], v[166:169], v[216:219], v[90:93]
	v_mfma_f32_16x16x32_bf16 v[78:81], v[134:137], v[224:227], v[78:81]
	v_mfma_f32_16x16x32_bf16 v[74:77], v[166:169], v[224:227], v[74:77]
	v_mfma_f32_16x16x32_bf16 v[118:121], v[174:177], v[196:199], v[118:121]
	v_mfma_f32_16x16x32_bf16 v[114:117], v[182:185], v[196:199], v[114:117]
	v_mfma_f32_16x16x32_bf16 v[102:105], v[174:177], v[204:207], v[102:105]
	v_mfma_f32_16x16x32_bf16 v[98:101], v[182:185], v[204:207], v[98:101]
	v_mfma_f32_16x16x32_bf16 v[86:89], v[174:177], v[212:215], v[86:89]
	v_mfma_f32_16x16x32_bf16 v[82:85], v[182:185], v[212:215], v[82:85]
	v_mfma_f32_16x16x32_bf16 v[70:73], v[174:177], v[220:223], v[70:73]
	v_mfma_f32_16x16x32_bf16 v[66:69], v[182:185], v[220:223], v[66:69]
	v_mfma_f32_16x16x32_bf16 v[118:121], v[178:181], v[200:203], v[118:121]
	v_mfma_f32_16x16x32_bf16 v[114:117], v[186:189], v[200:203], v[114:117]
	v_mfma_f32_16x16x32_bf16 v[102:105], v[178:181], v[208:211], v[102:105]
	v_mfma_f32_16x16x32_bf16 v[98:101], v[186:189], v[208:211], v[98:101]
	v_mfma_f32_16x16x32_bf16 v[86:89], v[178:181], v[216:219], v[86:89]
	v_mfma_f32_16x16x32_bf16 v[82:85], v[186:189], v[216:219], v[82:85]
	v_mfma_f32_16x16x32_bf16 v[70:73], v[178:181], v[224:227], v[70:73]
	v_mfma_f32_16x16x32_bf16 v[66:69], v[186:189], v[224:227], v[66:69]
	s_barrier
	s_setprio 0
	s_add_i32 s26, s60, s38
	s_mov_b32 m0, s26
	ds_read_b128 v[196:199], v164 offset:49152
	ds_read_b128 v[200:203], v164 offset:50176
	ds_read_b128 v[204:207], v164 offset:51200
	ds_read_b128 v[208:211], v164 offset:52224
	ds_read_b128 v[212:215], v164 offset:53248
	ds_read_b128 v[216:219], v164 offset:54272
	ds_read_b128 v[220:223], v164 offset:55296
	ds_read_b128 v[224:227], v164 offset:56320
	global_load_lds_dwordx4 v140, s[98:99]
	s_add_i32 m0, s26, 0x2000
	s_add_u32 s24, s24, 0xb0080
	s_addc_u32 s25, s25, 0
	s_add_i32 s26, s61, s38
	global_load_lds_dwordx4 v144, s[98:99]
	s_mov_b32 m0, s26
	s_nop 0
	global_load_lds_dwordx4 v140, s[24:25]
	s_add_i32 m0, s26, 0x2000
	s_nop 0
	global_load_lds_dwordx4 v144, s[24:25]
	s_mov_b32 m0, s44
	s_nop 0
	global_load_lds_dwordx4 v138, s[100:101]
	s_mov_b32 m0, s45
	s_nop 0
	global_load_lds_dwordx4 v142, s[100:101]
	s_waitcnt vmcnt(8)
	s_waitcnt lgkmcnt(0)
	s_setprio 1
	s_barrier
	v_mfma_f32_16x16x32_bf16 v[62:65], v[130:133], v[196:199], v[62:65]
	v_mfma_f32_16x16x32_bf16 v[58:61], v[154:157], v[196:199], v[58:61]
	v_mfma_f32_16x16x32_bf16 v[46:49], v[130:133], v[204:207], v[46:49]
	v_mfma_f32_16x16x32_bf16 v[42:45], v[154:157], v[204:207], v[42:45]
	v_mfma_f32_16x16x32_bf16 v[30:33], v[130:133], v[212:215], v[30:33]
	v_mfma_f32_16x16x32_bf16 v[26:29], v[154:157], v[212:215], v[26:29]
	v_mfma_f32_16x16x32_bf16 v[14:17], v[130:133], v[220:223], v[14:17]
	v_mfma_f32_16x16x32_bf16 v[10:13], v[154:157], v[220:223], v[10:13]
	v_mfma_f32_16x16x32_bf16 v[62:65], v[134:137], v[200:203], v[62:65]
	v_mfma_f32_16x16x32_bf16 v[58:61], v[166:169], v[200:203], v[58:61]
	v_mfma_f32_16x16x32_bf16 v[46:49], v[134:137], v[208:211], v[46:49]
	v_mfma_f32_16x16x32_bf16 v[42:45], v[166:169], v[208:211], v[42:45]
	v_mfma_f32_16x16x32_bf16 v[30:33], v[134:137], v[216:219], v[30:33]
	v_mfma_f32_16x16x32_bf16 v[26:29], v[166:169], v[216:219], v[26:29]
	v_mfma_f32_16x16x32_bf16 v[14:17], v[134:137], v[224:227], v[14:17]
	v_mfma_f32_16x16x32_bf16 v[10:13], v[166:169], v[224:227], v[10:13]
	v_mfma_f32_16x16x32_bf16 v[54:57], v[174:177], v[196:199], v[54:57]
	v_mfma_f32_16x16x32_bf16 v[50:53], v[182:185], v[196:199], v[50:53]
	v_mfma_f32_16x16x32_bf16 v[38:41], v[174:177], v[204:207], v[38:41]
	v_mfma_f32_16x16x32_bf16 v[34:37], v[182:185], v[204:207], v[34:37]
	v_mfma_f32_16x16x32_bf16 v[22:25], v[174:177], v[212:215], v[22:25]
	v_mfma_f32_16x16x32_bf16 v[18:21], v[182:185], v[212:215], v[18:21]
	v_mfma_f32_16x16x32_bf16 v[6:9], v[174:177], v[220:223], v[6:9]
	v_mfma_f32_16x16x32_bf16 v[2:5], v[182:185], v[220:223], v[2:5]
	v_mfma_f32_16x16x32_bf16 v[54:57], v[178:181], v[200:203], v[54:57]
	v_mfma_f32_16x16x32_bf16 v[50:53], v[186:189], v[200:203], v[50:53]
	v_mfma_f32_16x16x32_bf16 v[38:41], v[178:181], v[208:211], v[38:41]
	v_mfma_f32_16x16x32_bf16 v[34:37], v[186:189], v[208:211], v[34:37]
	v_mfma_f32_16x16x32_bf16 v[22:25], v[178:181], v[216:219], v[22:25]
	v_mfma_f32_16x16x32_bf16 v[18:21], v[186:189], v[216:219], v[18:21]
	v_mfma_f32_16x16x32_bf16 v[6:9], v[178:181], v[224:227], v[6:9]
	v_mfma_f32_16x16x32_bf16 v[2:5], v[186:189], v[224:227], v[2:5]
	s_barrier
	s_setprio 0
	s_add_i32 s59, s59, 2
	s_add_u32 s22, s22, 0x100
	s_addc_u32 s23, s23, 0
	s_add_u32 s57, s57, 0x100
	s_addc_u32 s58, s58, 0
	s_cmp_gt_u32 s59, 41
	s_cbranch_scc0 .LBB0_971
	s_and_b64 vcc, exec, s[18:19]
	s_cbranch_vccz .LBB0_974
	s_barrier
